# FFN gate/up epilogue: per-row rstd factors stashed in LDS per wave and reused when the next unit has the same row tile (skips 16 loads + reduction on ~9 of 11 units)
# speedup vs baseline: 1.0016x; 1.0016x over previous
; #define PG8_STAGE(bufoff, gbase, voff) do { _Pragma("unroll") for (int _i = 0; _i < 2; ++_i) \
;         __builtin_amdgcn_global_load_lds((const unsigned*)((const char*)(gbase) + (voff)[_i]), (PG8_LAS unsigned*)(lds + (bufoff) + ldsw + _i * 8192), 16, 0, 0); } while (0)
; #define PG8_WAIT_V(n) asm volatile("s_waitcnt vmcnt(" #n ")" ::: "memory")
; #define PG8_BAR __builtin_amdgcn_s_barrier()
; template <class Epi, class Sched, bool ALIGN_EPI = false, bool SP2 = false>
; __device__ __forceinline__ void gemm_phase(PG8_LAS unsigned char* lds, const Gemm g, const Sched& S, const Epi& E) {
;     int tid_l = threadIdx.x; asm volatile("" : "+v"(tid_l)); const int tid = tid_l, wid = __builtin_amdgcn_readfirstlane(tid >> 6), lane = tid & 63, wr = wid >> 2, wc = wid & 3, fr = lane & 15, fq = lane >> 4;
;     const int K = g.K, nt = K / BK;
;     unsigned voffA[2], voffB[2];
; #pragma unroll
;     for (int i = 0; i < 2; ++i) { int R, C; stage_rc(tid * 16 + i * 8192, R, C); const int Rb = Epi::PERM ? ((R & ~31) + perm32(R & 31)) : R;
;         voffA[i] = (unsigned)(R * K + C) * 2u; voffB[i] = (unsigned)(Rb * K + C) * 2u; }
;     const size_t kstep = (size_t)(BK * 2);
;     const size_t hstep = (size_t)HALF * K * 2;
;     const size_t tstep = 2 * hstep;
;     const unsigned ldsw = (unsigned)wid * 1024u;
;     const int aoff = lds_byte(wr * 64 + fr, fq * 8), boff = lds_byte(wc * 32 + fr, fq * 8);
;     ...
;         PG8_WAIT_V(2); PG8_BAR;
;         PG8_STAGE(PG8_SB(1, 0), cB + kstep, voffB); PG8_STAGE(PG8_SA(1, 0), cA + kstep, voffA); PG8_STAGE(PG8_SB(1, 1), cB + hstep + kstep, voffB);
;         PG8_WAIT_V(6); PG8_BAR;
.LBB0_411:
	v_mov_b32_e32 v237, 0
	v_bfe_u32 v15, v8, 4, 2
	v_and_b32_e32 v193, 15, v8
	v_lshlrev_b32_e32 v16, 4, v15
	v_lshlrev_b32_e32 v17, 2, v8
	s_lshl_b32 s1, s1, 5
	s_lshl_b32 s73, s2, 6
	v_lshl_or_b32 v16, v193, 6, v16
	s_lshl_b32 s2, s2, 13
	v_and_b32_e32 v17, 32, v17
	s_and_b32 s1, s1, 0x60
	s_add_i32 m0, s67, 0x18000
	v_lshl_add_u64 v[6:7], v[6:7], 0, s[20:21]
	v_bitop3_b32 v18, v16, s2, v17 bitop3:0xde
	s_lshl_b32 s2, s1, 7
	s_waitcnt vmcnt(2)
	s_barrier
	global_load_lds_dwordx4 v[6:7], off
	v_lshl_add_u64 v[4:5], v[4:5], 0, s[20:21]
	s_add_i32 m0, s67, 0x1a000
	s_add_i32 s74, s67, 0x8000
	s_add_i32 s75, s67, 0xa000
	global_load_lds_dwordx4 v[4:5], off
	v_lshl_add_u64 v[0:1], v[0:1], 0, s[20:21]
	s_mov_b32 m0, s74
	s_add_u32 s4, s40, 0x80080
	global_load_lds_dwordx4 v[0:1], off
	v_lshl_add_u64 v[0:1], v[2:3], 0, s[20:21]
	s_mov_b32 m0, s75
	s_addc_u32 s5, s41, 0
	global_load_lds_dwordx4 v[0:1], off
	s_add_i32 m0, s67, 0x1c000
	v_lshl_add_u64 v[0:1], s[4:5], 0, v[96:97]
	global_load_lds_dwordx4 v[0:1], off
	v_lshl_add_u64 v[0:1], s[4:5], 0, v[178:179]
	s_add_i32 m0, s67, 0x1e000
	s_cmpk_lt_u32 s0, 0x100
	global_load_lds_dwordx4 v[0:1], off
	v_lshlrev_b32_e32 v0, 5, v8
	v_and_b32_e32 v0, 0x60, v0
	v_mov_b32_e32 v1, v97
	v_lshl_add_u64 v[184:185], s[44:45], 0, v[0:1]
	v_lshlrev_b32_e32 v0, 15, v9
	v_and_b32_e32 v0, 0xffff0000, v0
	v_lshl_add_u32 v0, v10, 12, v0
	v_and_b32_e32 v1, 1, v9
	v_lshl_or_b32 v0, v1, 6, v0
	v_lshl_add_u32 v186, v11, 1, v0
	v_lshlrev_b32_e32 v0, 15, v13
	v_and_b32_e32 v0, 0xffff0000, v0
	s_waitcnt vmcnt(6)
	v_lshl_add_u32 v0, v12, 12, v0
	v_and_b32_e32 v1, 1, v13
	v_lshl_or_b32 v208, v15, 3, s1
	v_lshl_or_b32 v0, v1, 6, v0
	v_readlane_b32 s0, v254, 32
	v_bitop3_b32 v203, v16, s2, v17 bitop3:0xde
	s_cselect_b64 s[34:35], -1, 0
	v_bfe_u32 v206, v8, 2, 4
	v_lshlrev_b32_e32 v207, 4, v193
	v_mov_b32_e32 v187, v97
	v_lshl_add_u32 v188, v14, 1, v0
	v_mov_b32_e32 v189, v97
	s_mov_b32 s76, 0
	v_add_u32_e32 v209, 0, v18
	v_readlane_b32 s2, v253, 59
	s_mov_b32 s6, s0
	s_barrier
	v_readlane_b32 s1, v254, 33
	s_branch .LBB0_414

; __device__ __forceinline__ void tile_rstd(float (&rs)[2][4], const float* ssp, int rowtile, int wr, int fr, int fq) {
;     const int lane = fq * 16 + fr; f32x4 pa[2][4][2];
; #pragma unroll
;     for (int ai = 0; ai < 2; ++ai)
; #pragma unroll
;         for (int m = 0; m < 4; ++m) { const f32x4* p = (const f32x4*)(ssp + (size_t)(rowtile + wr * 64 + ai * HALF + m * 16 + (lane >> 2)) * 32 + (lane & 3) * 8); pa[ai][m][0] = p[0]; pa[ai][m][1] = p[1]; }
; #pragma unroll
;     for (int ai = 0; ai < 2; ++ai)
; #pragma unroll
;         for (int m = 0; m < 4; ++m) { const f32x4 a = pa[ai][m][0], b = pa[ai][m][1];
;             float t = ((a.x + a.y) + (a.z + a.w)) + ((b.x + b.y) + (b.z + b.w));
;             t += __shfl_xor(t, 1); t += __shfl_xor(t, 2);
;             rs[ai][m] = __shfl(rsqrtf(t * (1.0f / 2048.0f) + 1e-6f), fr * 4); }
.LBB0_420:
	v_readfirstlane_b32 s0, v237
	s_add_i32 s0, s0, -1
	s_cmp_eq_u32 s0, s6
	s_cbranch_scc1 .Lswi_hit
	v_lshrrev_b32_e32 v236, 6, v216
	v_and_b32_e32 v237, 15, v216
	v_lshlrev_b32_e32 v236, 9, v236
	v_lshl_add_u32 v236, v237, 5, v236
	v_add_u32_e32 v236, 0x21000, v236
	v_mov_b32_e32 v237, s6
	v_add_u32_e32 v237, 1, v237
	s_lshl_b32 s0, s6, 8
	s_add_i32 s0, s0, s73
	v_or_b32_e32 v130, s0, v206
	v_ashrrev_i32_e32 v131, 31, v130
	v_lshlrev_b64 v[132:133], 7, v[130:131]
	v_lshl_add_u64 v[132:133], v[184:185], 0, v[132:133]
	global_load_dwordx4 v[232:235], v[132:133], off
	global_load_dwordx4 v[242:245], v[132:133], off offset:16
	v_or_b32_e32 v132, 16, v130
	v_ashrrev_i32_e32 v133, 31, v132
	v_lshlrev_b64 v[132:133], 7, v[132:133]
	v_lshl_add_u64 v[132:133], v[184:185], 0, v[132:133]
	global_load_dwordx4 v[246:249], v[132:133], off
	global_load_dwordx4 v[228:231], v[132:133], off offset:16
	v_or_b32_e32 v132, 32, v130
	v_ashrrev_i32_e32 v133, 31, v132
	v_lshlrev_b64 v[132:133], 7, v[132:133]
	v_lshl_add_u64 v[132:133], v[184:185], 0, v[132:133]
	global_load_dwordx4 v[170:173], v[132:133], off
	global_load_dwordx4 v[174:177], v[132:133], off offset:16
	v_or_b32_e32 v132, 48, v130
	v_ashrrev_i32_e32 v133, 31, v132
	v_lshlrev_b64 v[132:133], 7, v[132:133]
	v_lshl_add_u64 v[132:133], v[184:185], 0, v[132:133]
	global_load_dwordx4 v[166:169], v[132:133], off
	global_load_dwordx4 v[162:165], v[132:133], off offset:16
	v_add_u32_e32 v132, 0x80, v130
	v_ashrrev_i32_e32 v133, 31, v132
	v_lshlrev_b64 v[132:133], 7, v[132:133]
	v_lshl_add_u64 v[132:133], v[184:185], 0, v[132:133]
	global_load_dwordx4 v[158:161], v[132:133], off
	global_load_dwordx4 v[154:157], v[132:133], off offset:16
	v_add_u32_e32 v132, 0x90, v130
	v_ashrrev_i32_e32 v133, 31, v132
	v_lshlrev_b64 v[132:133], 7, v[132:133]
	v_lshl_add_u64 v[132:133], v[184:185], 0, v[132:133]
	global_load_dwordx4 v[150:153], v[132:133], off
	global_load_dwordx4 v[146:149], v[132:133], off offset:16
	v_add_u32_e32 v132, 0xa0, v130
	v_ashrrev_i32_e32 v133, 31, v132
	v_lshlrev_b64 v[132:133], 7, v[132:133]
	v_add_u32_e32 v130, 0xb0, v130
	v_lshl_add_u64 v[132:133], v[184:185], 0, v[132:133]
	v_ashrrev_i32_e32 v131, 31, v130
	global_load_dwordx4 v[142:145], v[132:133], off
	global_load_dwordx4 v[138:141], v[132:133], off offset:16
	v_lshlrev_b64 v[130:131], 7, v[130:131]
	v_lshl_add_u64 v[130:131], v[184:185], 0, v[130:131]
	global_load_dwordx4 v[134:137], v[130:131], off
	s_nop 0
	global_load_dwordx4 v[130:133], v[130:131], off offset:16
	v_and_b32_e32 v192, 64, v220
	v_xor_b32_e32 v191, 1, v220
	v_add_u32_e32 v192, 64, v192
	v_cmp_lt_i32_e32 vcc, v191, v192
	v_or_b32_e32 v210, s0, v193
	v_readlane_b32 s0, v254, 63
	v_cndmask_b32_e32 v191, v220, v191, vcc
	v_lshlrev_b32_e32 v212, 2, v191
	v_xor_b32_e32 v191, 2, v220
	v_cmp_lt_i32_e32 vcc, v191, v192
	v_lshl_or_b32 v190, s2, 7, v208
	v_readlane_b32 s1, v255, 0
	v_cndmask_b32_e32 v191, v220, v191, vcc
	v_lshlrev_b32_e32 v211, 2, v191
	v_lshlrev_b32_e32 v191, 2, v220
	v_and_or_b32 v191, v191, s25, v207
	s_movk_i32 s2, 0x2c00
	s_waitcnt vmcnt(0) lgkmcnt(0)
	v_mov_b32_e32 v204, v232
	v_mov_b32_e32 v205, v242
	v_mov_b32_e32 v242, v233
	v_mov_b32_e32 v214, v234
	v_mov_b32_e32 v215, v244
	v_mov_b32_e32 v244, v235
	v_pk_add_f32 v[204:205], v[204:205], v[242:243]
	v_pk_add_f32 v[214:215], v[214:215], v[244:245]
	s_nop 0
	v_pk_add_f32 v[204:205], v[204:205], v[214:215]
	v_mov_b32_e32 v214, v246
	v_mov_b32_e32 v215, v228
	v_mov_b32_e32 v228, v247
	v_pk_add_f32 v[214:215], v[214:215], v[228:229]
	v_mov_b32_e32 v228, v248
	v_mov_b32_e32 v229, v230
	v_mov_b32_e32 v230, v249
	v_pk_add_f32 v[228:229], v[228:229], v[230:231]
	s_nop 0
	v_pk_add_f32 v[214:215], v[214:215], v[228:229]
	v_mov_b32_e32 v229, v204
	v_mov_b32_e32 v228, v214
	v_mov_b32_e32 v204, v215
	v_pk_add_f32 v[204:205], v[228:229], v[204:205]
	ds_bpermute_b32 v215, v212, v205
	ds_bpermute_b32 v214, v212, v204
	s_waitcnt lgkmcnt(0)
	v_pk_add_f32 v[204:205], v[204:205], v[214:215]
	ds_bpermute_b32 v215, v211, v205
	ds_bpermute_b32 v214, v211, v204
	s_waitcnt lgkmcnt(0)
	v_pk_add_f32 v[214:215], v[204:205], v[214:215]
	v_mov_b64_e32 v[204:205], s[24:25]
	v_pk_fma_f32 v[214:215], v[214:215], s[18:19], v[204:205] op_sel_hi:[1,0,0]
	s_nop 0
	v_mul_f32_e32 v192, 0x4b800000, v215
	v_cmp_gt_f32_e64 s[40:41], s12, v215
	v_cmp_gt_f32_e32 vcc, s12, v214
	s_nop 0
	v_cndmask_b32_e64 v192, v215, v192, s[40:41]
	v_rsq_f32_e32 v192, v192
	v_mov_b32_e32 v215, v174
	v_mov_b32_e32 v174, v171
	v_mul_f32_e32 v202, 0x45800000, v192
	v_cndmask_b32_e64 v192, v192, v202, s[40:41]
	ds_bpermute_b32 v202, v191, v192
	v_mul_f32_e32 v192, 0x4b800000, v214
	v_cndmask_b32_e32 v192, v214, v192, vcc
	v_mov_b32_e32 v214, v170
	v_pk_add_f32 v[170:171], v[214:215], v[174:175]
	v_mov_b32_e32 v174, v172
	v_mov_b32_e32 v175, v176
	v_mov_b32_e32 v176, v173
	v_pk_add_f32 v[172:173], v[174:175], v[176:177]
	s_waitcnt lgkmcnt(0)
; __device__ __forceinline__ unsigned pk_bf16(float lo, float hi) { f32x2e v = {lo, hi}; bf16x2e b = __builtin_convertvector(v, bf16x2e); return __builtin_bit_cast(unsigned, b); }
; __device__ __forceinline__ float silu_mul(float g, float u) { return g * __builtin_amdgcn_rcpf(1.0f + __builtin_amdgcn_exp2f(-1.4426950408889634f * g)) * u; }
; __device__ __forceinline__ void tile_rstd(float (&rs)[2][4], const float* ssp, int rowtile, int wr, int fr, int fq) {
;     ...
;         for (int m = 0; m < 4; ++m) { const f32x4 a = pa[ai][m][0], b = pa[ai][m][1];
;             float t = ((a.x + a.y) + (a.z + a.w)) + ((b.x + b.y) + (b.z + b.w));
;             t += __shfl_xor(t, 1); t += __shfl_xor(t, 2);
;             rs[ai][m] = __shfl(rsqrtf(t * (1.0f / 2048.0f) + 1e-6f), fr * 4); }
;     __device__ __forceinline__ void operator()(const f32x4 (&acc)[2][2][4][2], const Unit& u, int wr, int wc, int fr, int fq) const {
;     ...
;             for (int m = 0; m < 4; ++m) { bf16_t* rowp = O + (size_t)(row0 + ai * HALF + m * 16) * ldc + col0;
;                 const float rs = rsa[ai][m];
;                 const f32x4 g0 = acc[ai][0][m][0] * rs, g1 = acc[ai][0][m][1] * rs, u0 = acc[ai][1][m][0] * rs, u1 = acc[ai][1][m][1] * rs;
;                 u32x4 w; w.x = pk_bf16(silu_mul(g0[0], u0[0]), silu_mul(g0[1], u0[1])); w.y = pk_bf16(silu_mul(g0[2], u0[2]), silu_mul(g0[3], u0[3]));
;                 w.z = pk_bf16(silu_mul(g1[0], u1[0]), silu_mul(g1[1], u1[1])); w.w = pk_bf16(silu_mul(g1[2], u1[2]), silu_mul(g1[3], u1[3]));
	ds_write_b32 v236, v202
	v_pk_mul_f32 v[126:127], v[126:127], v[202:203] op_sel_hi:[1,0]
	v_pk_add_f32 v[170:171], v[170:171], v[172:173]
	v_mov_b32_e32 v172, v166
	v_mov_b32_e32 v173, v162
	v_mov_b32_e32 v162, v167
	v_mov_b32_e32 v166, v168
	v_mov_b32_e32 v167, v164
	v_mov_b32_e32 v164, v169
	v_pk_add_f32 v[164:165], v[166:167], v[164:165]
	v_mov_b32_e32 v166, v158
	v_mov_b32_e32 v167, v154
	v_mov_b32_e32 v154, v159
	v_mov_b32_e32 v158, v160
	v_mov_b32_e32 v159, v156
	v_mov_b32_e32 v156, v161
	v_pk_add_f32 v[154:155], v[166:167], v[154:155]
	v_pk_add_f32 v[156:157], v[158:159], v[156:157]
	v_pk_mul_f32 v[118:119], v[118:119], v[202:203] op_sel_hi:[1,0]
	v_pk_add_f32 v[154:155], v[154:155], v[156:157]
	v_mov_b32_e32 v156, v150
	v_mov_b32_e32 v157, v146
	v_mov_b32_e32 v146, v151
	v_mov_b32_e32 v150, v152
	v_mov_b32_e32 v151, v148
	v_mov_b32_e32 v148, v153
	v_pk_add_f32 v[148:149], v[150:151], v[148:149]
	v_mov_b32_e32 v150, v142
	v_mov_b32_e32 v151, v138
	v_mov_b32_e32 v138, v143
	v_mov_b32_e32 v142, v144
	v_mov_b32_e32 v143, v140
	v_mov_b32_e32 v140, v145
	v_pk_add_f32 v[138:139], v[150:151], v[138:139]
	v_pk_add_f32 v[140:141], v[142:143], v[140:141]
	v_pk_add_f32 v[162:163], v[172:173], v[162:163]
	v_pk_add_f32 v[138:139], v[138:139], v[140:141]
	v_mov_b32_e32 v140, v134
	v_mov_b32_e32 v141, v130
	v_mov_b32_e32 v130, v135
	v_pk_add_f32 v[130:131], v[140:141], v[130:131]
	v_pk_mul_f32 v[140:141], v[116:117], v[202:203] op_sel_hi:[1,0]
	v_pk_mul_f32 v[116:117], v[114:115], v[202:203] op_sel_hi:[1,0]
	v_mul_f32_e32 v114, 0xbfb8aa3b, v126
	v_mul_f32_e32 v115, 0xbfb8aa3b, v127
	v_exp_f32_e32 v114, v114
	v_exp_f32_e32 v115, v115
	v_pk_mul_f32 v[128:129], v[128:129], v[202:203] op_sel_hi:[1,0]
	v_pk_add_f32 v[162:163], v[162:163], v[164:165]
	v_add_f32_e32 v114, 1.0, v114
	v_add_f32_e32 v115, 1.0, v115
	v_rcp_f32_e32 v114, v114
	v_rcp_f32_e32 v115, v115
	v_mov_b32_e32 v164, v162
	v_mov_b32_e32 v165, v170
	v_mov_b32_e32 v170, v163
	v_pk_mul_f32 v[114:115], v[126:127], v[114:115]
	v_pk_add_f32 v[162:163], v[164:165], v[170:171]
	v_pk_mul_f32 v[114:115], v[118:119], v[114:115]
	ds_bpermute_b32 v165, v212, v163
	v_cvt_pk_bf16_f32 v114, v114, v115
	v_mul_f32_e32 v115, 0xbfb8aa3b, v128
	v_exp_f32_e32 v115, v115
	ds_bpermute_b32 v164, v212, v162
	v_pk_add_f32 v[146:147], v[156:157], v[146:147]
	v_mov_b32_e32 v134, v136
	v_add_f32_e32 v115, 1.0, v115
	v_rcp_f32_e32 v118, v115
	v_mul_f32_e32 v115, 0xbfb8aa3b, v129
	v_pk_add_f32 v[146:147], v[146:147], v[148:149]
	v_exp_f32_e32 v115, v115
	s_waitcnt lgkmcnt(0)
	v_pk_add_f32 v[162:163], v[162:163], v[164:165]
	v_mov_b32_e32 v148, v146
	v_mov_b32_e32 v149, v154
	v_mov_b32_e32 v154, v147
	ds_bpermute_b32 v165, v211, v163
	ds_bpermute_b32 v164, v211, v162
	v_pk_add_f32 v[146:147], v[148:149], v[154:155]
	ds_bpermute_b32 v149, v212, v147
	ds_bpermute_b32 v148, v212, v146
	v_add_f32_e32 v115, 1.0, v115
	v_mov_b32_e32 v135, v132
	v_mov_b32_e32 v132, v137
	v_rcp_f32_e32 v119, v115
	v_pk_add_f32 v[132:133], v[134:135], v[132:133]
	s_waitcnt lgkmcnt(2)
	v_pk_add_f32 v[162:163], v[162:163], v[164:165]
	v_pk_add_f32 v[130:131], v[130:131], v[132:133]
	v_pk_fma_f32 v[162:163], v[162:163], s[18:19], v[204:205] op_sel_hi:[1,0,0]
	s_waitcnt lgkmcnt(0)
	v_pk_add_f32 v[146:147], v[146:147], v[148:149]
	v_mov_b32_e32 v132, v130
	v_mov_b32_e32 v133, v138
	v_mov_b32_e32 v138, v131
	v_mul_f32_e32 v164, 0x4b800000, v163
	v_cmp_gt_f32_e64 s[40:41], s12, v163
	ds_bpermute_b32 v149, v211, v147
	ds_bpermute_b32 v148, v211, v146
	v_pk_add_f32 v[130:131], v[132:133], v[138:139]
	v_pk_mul_f32 v[120:121], v[120:121], v[202:203] op_sel_hi:[1,0]
	v_pk_mul_f32 v[118:119], v[128:129], v[118:119]
	v_cndmask_b32_e64 v163, v163, v164, s[40:41]
	ds_bpermute_b32 v133, v212, v131
	ds_bpermute_b32 v132, v212, v130
	v_pk_mul_f32 v[122:123], v[122:123], v[202:203] op_sel_hi:[1,0]
	v_pk_mul_f32 v[118:119], v[120:121], v[118:119]
	v_rsq_f32_e32 v163, v163
	v_cvt_pk_bf16_f32 v115, v118, v119
	v_mul_f32_e32 v118, 0xbfb8aa3b, v122
	v_mul_f32_e32 v119, 0xbfb8aa3b, v123
	v_rsq_f32_e32 v192, v192
	v_exp_f32_e32 v118, v118
	v_exp_f32_e32 v119, v119
	s_waitcnt lgkmcnt(2)
	v_pk_add_f32 v[146:147], v[146:147], v[148:149]
	v_mul_f32_e32 v164, 0x45800000, v163
	v_pk_fma_f32 v[146:147], v[146:147], s[18:19], v[204:205] op_sel_hi:[1,0,0]
	s_waitcnt lgkmcnt(0)
	v_pk_add_f32 v[130:131], v[130:131], v[132:133]
	v_mul_f32_e32 v213, 0x45800000, v192
	v_cndmask_b32_e64 v163, v163, v164, s[40:41]
	v_mul_f32_e32 v148, 0x4b800000, v147
	v_cmp_gt_f32_e64 s[40:41], s12, v147
	ds_bpermute_b32 v133, v211, v131
	ds_bpermute_b32 v132, v211, v130
	v_add_f32_e32 v118, 1.0, v118
	v_add_f32_e32 v119, 1.0, v119
	v_cndmask_b32_e32 v192, v192, v213, vcc
	v_cmp_gt_f32_e32 vcc, s12, v162
	ds_bpermute_b32 v164, v191, v163
	v_mul_f32_e32 v163, 0x4b800000, v162
	v_cndmask_b32_e64 v147, v147, v148, s[40:41]
	v_rcp_f32_e32 v118, v118
	v_rcp_f32_e32 v119, v119
	v_cndmask_b32_e32 v162, v162, v163, vcc
	v_rsq_f32_e32 v147, v147
	v_rsq_f32_e32 v162, v162
	s_waitcnt lgkmcnt(1)
; __device__ __forceinline__ unsigned pk_bf16(float lo, float hi) { f32x2e v = {lo, hi}; bf16x2e b = __builtin_convertvector(v, bf16x2e); return __builtin_bit_cast(unsigned, b); }
; __device__ __forceinline__ float silu_mul(float g, float u) { return g * __builtin_amdgcn_rcpf(1.0f + __builtin_amdgcn_exp2f(-1.4426950408889634f * g)) * u; }
; __device__ __forceinline__ void tile_rstd(float (&rs)[2][4], const float* ssp, int rowtile, int wr, int fr, int fq) {
;     ...
;         for (int m = 0; m < 4; ++m) { const f32x4 a = pa[ai][m][0], b = pa[ai][m][1];
;             float t = ((a.x + a.y) + (a.z + a.w)) + ((b.x + b.y) + (b.z + b.w));
;             t += __shfl_xor(t, 1); t += __shfl_xor(t, 2);
;             rs[ai][m] = __shfl(rsqrtf(t * (1.0f / 2048.0f) + 1e-6f), fr * 4); }
;     __device__ __forceinline__ void operator()(const f32x4 (&acc)[2][2][4][2], const Unit& u, int wr, int wc, int fr, int fq) const {
;     ...
;             for (int m = 0; m < 4; ++m) { bf16_t* rowp = O + (size_t)(row0 + ai * HALF + m * 16) * ldc + col0;
;                 const float rs = rsa[ai][m];
;                 const f32x4 g0 = acc[ai][0][m][0] * rs, g1 = acc[ai][0][m][1] * rs, u0 = acc[ai][1][m][0] * rs, u1 = acc[ai][1][m][1] * rs;
;                 u32x4 w; w.x = pk_bf16(silu_mul(g0[0], u0[0]), silu_mul(g0[1], u0[1])); w.y = pk_bf16(silu_mul(g0[2], u0[2]), silu_mul(g0[3], u0[3]));
;                 w.z = pk_bf16(silu_mul(g1[0], u1[0]), silu_mul(g1[1], u1[1])); w.w = pk_bf16(silu_mul(g1[2], u1[2]), silu_mul(g1[3], u1[3]));
;                 *(u32x4*)rowp = w; }
	v_pk_add_f32 v[130:131], v[130:131], v[132:133]
	v_pk_mul_f32 v[118:119], v[122:123], v[118:119]
	v_mul_f32_e32 v148, 0x45800000, v147
	v_pk_fma_f32 v[130:131], v[130:131], s[18:19], v[204:205] op_sel_hi:[1,0,0]
	v_pk_mul_f32 v[124:125], v[124:125], v[202:203] op_sel_hi:[1,0]
	v_pk_mul_f32 v[116:117], v[116:117], v[118:119]
	v_mul_f32_e32 v163, 0x45800000, v162
	v_cndmask_b32_e64 v147, v147, v148, s[40:41]
	v_mul_f32_e32 v132, 0x4b800000, v131
	v_cmp_gt_f32_e64 s[40:41], s12, v131
	v_cvt_pk_bf16_f32 v116, v116, v117
	v_mul_f32_e32 v117, 0xbfb8aa3b, v124
	v_cndmask_b32_e32 v162, v162, v163, vcc
	v_cmp_gt_f32_e32 vcc, s12, v146
	ds_bpermute_b32 v148, v191, v147
	v_mul_f32_e32 v147, 0x4b800000, v146
	v_cndmask_b32_e64 v131, v131, v132, s[40:41]
	v_exp_f32_e32 v117, v117
	v_cndmask_b32_e32 v146, v146, v147, vcc
	v_rsq_f32_e32 v131, v131
	v_rsq_f32_e32 v146, v146
	v_add_f32_e32 v117, 1.0, v117
	v_rcp_f32_e32 v118, v117
	v_mul_f32_e32 v132, 0x45800000, v131
	v_mul_f32_e32 v117, 0xbfb8aa3b, v125
	v_mul_f32_e32 v147, 0x45800000, v146
	v_cndmask_b32_e64 v131, v131, v132, s[40:41]
	v_exp_f32_e32 v117, v117
	v_cndmask_b32_e32 v146, v146, v147, vcc
	v_cmp_gt_f32_e32 vcc, s12, v130
	ds_bpermute_b32 v136, v191, v131
	v_mul_f32_e32 v131, 0x4b800000, v130
	v_cndmask_b32_e32 v130, v130, v131, vcc
	v_rsq_f32_e32 v130, v130
	v_add_f32_e32 v117, 1.0, v117
	v_rcp_f32_e32 v119, v117
	ds_bpermute_b32 v192, v191, v192
	v_mul_f32_e32 v131, 0x45800000, v130
	v_cndmask_b32_e32 v130, v130, v131, vcc
	ds_bpermute_b32 v162, v191, v162
	ds_bpermute_b32 v146, v191, v146
	ds_bpermute_b32 v130, v191, v130
	v_ashrrev_i32_e32 v191, 31, v190
	v_mov_b64_e32 v[132:133], s[0:1]
	v_pk_mul_f32 v[118:119], v[124:125], v[118:119]
	v_mad_i64_i32 v[138:139], s[0:1], v210, s2, v[132:133]
	v_lshlrev_b64 v[134:135], 1, v[190:191]
	v_pk_mul_f32 v[118:119], v[140:141], v[118:119]
	v_lshl_add_u64 v[138:139], v[138:139], 0, v[134:135]
	v_cvt_pk_bf16_f32 v117, v118, v119
	s_waitcnt lgkmcnt(3)
	ds_write_b32 v236, v192 offset:16
	v_pk_mul_f32 v[110:111], v[110:111], v[192:193] op_sel_hi:[1,0]
	global_store_dwordx4 v[138:139], v[114:117], off
	v_pk_mul_f32 v[102:103], v[102:103], v[192:193] op_sel_hi:[1,0]
	v_pk_mul_f32 v[112:113], v[112:113], v[192:193] op_sel_hi:[1,0]
	v_pk_mul_f32 v[116:117], v[100:101], v[192:193] op_sel_hi:[1,0]
	v_pk_mul_f32 v[100:101], v[98:99], v[192:193] op_sel_hi:[1,0]
	v_mul_f32_e32 v98, 0xbfb8aa3b, v110
	v_mul_f32_e32 v99, 0xbfb8aa3b, v111
	v_exp_f32_e32 v98, v98
	v_exp_f32_e32 v99, v99
	v_pk_mul_f32 v[104:105], v[104:105], v[192:193] op_sel_hi:[1,0]
	v_pk_mul_f32 v[106:107], v[106:107], v[192:193] op_sel_hi:[1,0]
	v_add_f32_e32 v98, 1.0, v98
	v_add_f32_e32 v99, 1.0, v99
	v_rcp_f32_e32 v98, v98
	v_rcp_f32_e32 v99, v99
	v_pk_mul_f32 v[108:109], v[108:109], v[192:193] op_sel_hi:[1,0]
	v_or_b32_e32 v114, 16, v210
	v_mad_i64_i32 v[114:115], s[0:1], v114, s2, v[132:133]
	v_pk_mul_f32 v[98:99], v[110:111], v[98:99]
	v_lshl_add_u64 v[114:115], v[114:115], 0, v[134:135]
	v_pk_mul_f32 v[98:99], v[102:103], v[98:99]
	ds_write_b32 v236, v164 offset:4
	v_pk_mul_f32 v[92:93], v[92:93], v[164:165] op_sel_hi:[1,0]
	v_cvt_pk_bf16_f32 v98, v98, v99
	v_mul_f32_e32 v99, 0xbfb8aa3b, v112
	v_exp_f32_e32 v99, v99
	v_pk_mul_f32 v[84:85], v[84:85], v[164:165] op_sel_hi:[1,0]
	v_pk_mul_f32 v[94:95], v[94:95], v[164:165] op_sel_hi:[1,0]
	v_pk_mul_f32 v[86:87], v[86:87], v[164:165] op_sel_hi:[1,0]
	v_add_f32_e32 v99, 1.0, v99
	v_rcp_f32_e32 v102, v99
	v_mul_f32_e32 v99, 0xbfb8aa3b, v113
	v_exp_f32_e32 v99, v99
	v_pk_mul_f32 v[88:89], v[88:89], v[164:165] op_sel_hi:[1,0]
	v_pk_mul_f32 v[90:91], v[90:91], v[164:165] op_sel_hi:[1,0]
	s_waitcnt lgkmcnt(0)
	ds_write_b32 v236, v162 offset:20
	v_pk_mul_f32 v[76:77], v[76:77], v[162:163] op_sel_hi:[1,0]
	v_add_f32_e32 v99, 1.0, v99
	v_rcp_f32_e32 v103, v99
	v_pk_mul_f32 v[68:69], v[68:69], v[162:163] op_sel_hi:[1,0]
	v_pk_mul_f32 v[78:79], v[78:79], v[162:163] op_sel_hi:[1,0]
	v_pk_mul_f32 v[70:71], v[70:71], v[162:163] op_sel_hi:[1,0]
	v_pk_mul_f32 v[102:103], v[112:113], v[102:103]
	v_pk_mul_f32 v[72:73], v[72:73], v[162:163] op_sel_hi:[1,0]
	v_pk_mul_f32 v[102:103], v[104:105], v[102:103]
	v_pk_mul_f32 v[74:75], v[74:75], v[162:163] op_sel_hi:[1,0]
	v_cvt_pk_bf16_f32 v99, v102, v103
	v_mul_f32_e32 v102, 0xbfb8aa3b, v106
	v_mul_f32_e32 v103, 0xbfb8aa3b, v107
	v_exp_f32_e32 v102, v102
	v_exp_f32_e32 v103, v103
	ds_write_b32 v236, v148 offset:8
	v_pk_mul_f32 v[60:61], v[60:61], v[148:149] op_sel_hi:[1,0]
	v_pk_mul_f32 v[52:53], v[52:53], v[148:149] op_sel_hi:[1,0]
	v_add_f32_e32 v102, 1.0, v102
	v_add_f32_e32 v103, 1.0, v103
	v_rcp_f32_e32 v102, v102
	v_rcp_f32_e32 v103, v103
	v_pk_mul_f32 v[62:63], v[62:63], v[148:149] op_sel_hi:[1,0]
	v_pk_mul_f32 v[54:55], v[54:55], v[148:149] op_sel_hi:[1,0]
	v_pk_mul_f32 v[56:57], v[56:57], v[148:149] op_sel_hi:[1,0]
	v_pk_mul_f32 v[102:103], v[106:107], v[102:103]
	v_pk_mul_f32 v[58:59], v[58:59], v[148:149] op_sel_hi:[1,0]
	v_pk_mul_f32 v[100:101], v[100:101], v[102:103]
	ds_write_b32 v236, v146 offset:24
	v_pk_mul_f32 v[44:45], v[44:45], v[146:147] op_sel_hi:[1,0]
	v_cvt_pk_bf16_f32 v100, v100, v101
	v_mul_f32_e32 v101, 0xbfb8aa3b, v108
	v_exp_f32_e32 v101, v101
	v_pk_mul_f32 v[36:37], v[36:37], v[146:147] op_sel_hi:[1,0]
	v_pk_mul_f32 v[46:47], v[46:47], v[146:147] op_sel_hi:[1,0]
	v_pk_mul_f32 v[38:39], v[38:39], v[146:147] op_sel_hi:[1,0]
	v_add_f32_e32 v101, 1.0, v101
	v_rcp_f32_e32 v102, v101
	v_mul_f32_e32 v101, 0xbfb8aa3b, v109
	v_exp_f32_e32 v101, v101
	v_pk_mul_f32 v[40:41], v[40:41], v[146:147] op_sel_hi:[1,0]
	v_pk_mul_f32 v[42:43], v[42:43], v[146:147] op_sel_hi:[1,0]
	ds_write_b32 v236, v136 offset:12
; __device__ __forceinline__ unsigned pk_bf16(float lo, float hi) { f32x2e v = {lo, hi}; bf16x2e b = __builtin_convertvector(v, bf16x2e); return __builtin_bit_cast(unsigned, b); }
; __device__ __forceinline__ float silu_mul(float g, float u) { return g * __builtin_amdgcn_rcpf(1.0f + __builtin_amdgcn_exp2f(-1.4426950408889634f * g)) * u; }
;     __device__ __forceinline__ void operator()(const f32x4 (&acc)[2][2][4][2], const Unit& u, int wr, int wc, int fr, int fq) const {
;     ...
;             for (int m = 0; m < 4; ++m) { bf16_t* rowp = O + (size_t)(row0 + ai * HALF + m * 16) * ldc + col0;
;                 const float rs = rsa[ai][m];
;                 const f32x4 g0 = acc[ai][0][m][0] * rs, g1 = acc[ai][0][m][1] * rs, u0 = acc[ai][1][m][0] * rs, u1 = acc[ai][1][m][1] * rs;
;                 u32x4 w; w.x = pk_bf16(silu_mul(g0[0], u0[0]), silu_mul(g0[1], u0[1])); w.y = pk_bf16(silu_mul(g0[2], u0[2]), silu_mul(g0[3], u0[3]));
;                 w.z = pk_bf16(silu_mul(g1[0], u1[0]), silu_mul(g1[1], u1[1])); w.w = pk_bf16(silu_mul(g1[2], u1[2]), silu_mul(g1[3], u1[3]));
;                 *(u32x4*)rowp = w; }
	v_pk_mul_f32 v[28:29], v[28:29], v[136:137] op_sel_hi:[1,0]
	v_add_f32_e32 v101, 1.0, v101
	v_rcp_f32_e32 v103, v101
	v_pk_mul_f32 v[20:21], v[20:21], v[136:137] op_sel_hi:[1,0]
	v_pk_mul_f32 v[30:31], v[30:31], v[136:137] op_sel_hi:[1,0]
	v_pk_mul_f32 v[22:23], v[22:23], v[136:137] op_sel_hi:[1,0]
	v_pk_mul_f32 v[102:103], v[108:109], v[102:103]
	v_pk_mul_f32 v[24:25], v[24:25], v[136:137] op_sel_hi:[1,0]
	v_pk_mul_f32 v[102:103], v[116:117], v[102:103]
	v_pk_mul_f32 v[26:27], v[26:27], v[136:137] op_sel_hi:[1,0]
	v_cvt_pk_bf16_f32 v101, v102, v103
	global_store_dwordx4 v[114:115], v[98:101], off
	ds_write_b32 v236, v130 offset:28
	v_pk_mul_f32 v[12:13], v[12:13], v[130:131] op_sel_hi:[1,0]
	v_pk_mul_f32 v[4:5], v[4:5], v[130:131] op_sel_hi:[1,0]
	v_pk_mul_f32 v[100:101], v[82:83], v[164:165] op_sel_hi:[1,0]
	v_pk_mul_f32 v[82:83], v[80:81], v[164:165] op_sel_hi:[1,0]
	v_mul_f32_e32 v80, 0xbfb8aa3b, v92
	v_mul_f32_e32 v81, 0xbfb8aa3b, v93
	v_exp_f32_e32 v80, v80
	v_exp_f32_e32 v81, v81
	v_or_b32_e32 v98, 32, v210
	v_mad_i64_i32 v[98:99], s[0:1], v98, s2, v[132:133]
	v_add_f32_e32 v80, 1.0, v80
	v_add_f32_e32 v81, 1.0, v81
	v_rcp_f32_e32 v80, v80
	v_rcp_f32_e32 v81, v81
	v_lshl_add_u64 v[98:99], v[98:99], 0, v[134:135]
	v_pk_mul_f32 v[14:15], v[14:15], v[130:131] op_sel_hi:[1,0]
	v_pk_mul_f32 v[6:7], v[6:7], v[130:131] op_sel_hi:[1,0]
	v_pk_mul_f32 v[80:81], v[92:93], v[80:81]
	v_pk_mul_f32 v[8:9], v[8:9], v[130:131] op_sel_hi:[1,0]
	v_pk_mul_f32 v[80:81], v[84:85], v[80:81]
	v_pk_mul_f32 v[10:11], v[10:11], v[130:131] op_sel_hi:[1,0]
	v_cvt_pk_bf16_f32 v80, v80, v81
	v_mul_f32_e32 v81, 0xbfb8aa3b, v94
	v_exp_f32_e32 v81, v81
	s_andn2_b64 vcc, exec, s[38:39]
	v_add_f32_e32 v81, 1.0, v81
	v_rcp_f32_e32 v84, v81
	v_mul_f32_e32 v81, 0xbfb8aa3b, v95
	v_exp_f32_e32 v81, v81
	s_nop 0
	v_add_f32_e32 v81, 1.0, v81
	v_rcp_f32_e32 v85, v81
	s_nop 0
	v_pk_mul_f32 v[84:85], v[94:95], v[84:85]
	s_nop 0
	v_pk_mul_f32 v[84:85], v[86:87], v[84:85]
	s_nop 0
	v_cvt_pk_bf16_f32 v81, v84, v85
	v_mul_f32_e32 v84, 0xbfb8aa3b, v88
	v_mul_f32_e32 v85, 0xbfb8aa3b, v89
	v_exp_f32_e32 v84, v84
	v_exp_f32_e32 v85, v85
	v_add_f32_e32 v84, 1.0, v84
	v_add_f32_e32 v85, 1.0, v85
	v_rcp_f32_e32 v84, v84
	v_rcp_f32_e32 v85, v85
	s_nop 0
	v_pk_mul_f32 v[84:85], v[88:89], v[84:85]
	s_nop 0
	v_pk_mul_f32 v[82:83], v[82:83], v[84:85]
	s_nop 0
	v_cvt_pk_bf16_f32 v82, v82, v83
	v_mul_f32_e32 v83, 0xbfb8aa3b, v90
	v_exp_f32_e32 v83, v83
	s_nop 0
	v_add_f32_e32 v83, 1.0, v83
	v_rcp_f32_e32 v84, v83
	v_mul_f32_e32 v83, 0xbfb8aa3b, v91
	v_exp_f32_e32 v83, v83
	s_nop 0
	v_add_f32_e32 v83, 1.0, v83
	v_rcp_f32_e32 v85, v83
	s_nop 0
	v_pk_mul_f32 v[84:85], v[90:91], v[84:85]
	s_nop 0
	v_pk_mul_f32 v[84:85], v[100:101], v[84:85]
	s_nop 0
	v_cvt_pk_bf16_f32 v83, v84, v85
	global_store_dwordx4 v[98:99], v[80:83], off
	s_nop 1
	v_pk_mul_f32 v[82:83], v[66:67], v[162:163] op_sel_hi:[1,0]
	v_pk_mul_f32 v[66:67], v[64:65], v[162:163] op_sel_hi:[1,0]
	v_mul_f32_e32 v64, 0xbfb8aa3b, v76
	v_mul_f32_e32 v65, 0xbfb8aa3b, v77
	v_exp_f32_e32 v64, v64
	v_exp_f32_e32 v65, v65
	v_or_b32_e32 v80, 48, v210
	v_mad_i64_i32 v[80:81], s[0:1], v80, s2, v[132:133]
	v_add_f32_e32 v64, 1.0, v64
	v_add_f32_e32 v65, 1.0, v65
	v_rcp_f32_e32 v64, v64
	v_rcp_f32_e32 v65, v65
	v_lshl_add_u64 v[80:81], v[80:81], 0, v[134:135]
	v_pk_mul_f32 v[64:65], v[76:77], v[64:65]
	s_nop 0
	v_pk_mul_f32 v[64:65], v[68:69], v[64:65]
	s_nop 0
	v_cvt_pk_bf16_f32 v64, v64, v65
	v_mul_f32_e32 v65, 0xbfb8aa3b, v78
	v_exp_f32_e32 v65, v65
	s_nop 0
	v_add_f32_e32 v65, 1.0, v65
	v_rcp_f32_e32 v68, v65
	v_mul_f32_e32 v65, 0xbfb8aa3b, v79
	v_exp_f32_e32 v65, v65
	s_nop 0
	v_add_f32_e32 v65, 1.0, v65
	v_rcp_f32_e32 v69, v65
	s_nop 0
	v_pk_mul_f32 v[68:69], v[78:79], v[68:69]
	s_nop 0
	v_pk_mul_f32 v[68:69], v[70:71], v[68:69]
	s_nop 0
	v_cvt_pk_bf16_f32 v65, v68, v69
	v_mul_f32_e32 v68, 0xbfb8aa3b, v72
	v_mul_f32_e32 v69, 0xbfb8aa3b, v73
	v_exp_f32_e32 v68, v68
	v_exp_f32_e32 v69, v69
	v_add_f32_e32 v68, 1.0, v68
	v_add_f32_e32 v69, 1.0, v69
	v_rcp_f32_e32 v68, v68
	v_rcp_f32_e32 v69, v69
	s_nop 0
	v_pk_mul_f32 v[68:69], v[72:73], v[68:69]
	s_nop 0
	v_pk_mul_f32 v[66:67], v[66:67], v[68:69]
	s_nop 0
	v_cvt_pk_bf16_f32 v66, v66, v67
	v_mul_f32_e32 v67, 0xbfb8aa3b, v74
	v_exp_f32_e32 v67, v67
	s_nop 0
	v_add_f32_e32 v67, 1.0, v67
	v_rcp_f32_e32 v68, v67
	v_mul_f32_e32 v67, 0xbfb8aa3b, v75
	v_exp_f32_e32 v67, v67
	s_nop 0
	v_add_f32_e32 v67, 1.0, v67
	v_rcp_f32_e32 v69, v67
	s_nop 0
	v_pk_mul_f32 v[68:69], v[74:75], v[68:69]
	s_nop 0
	v_pk_mul_f32 v[68:69], v[82:83], v[68:69]
	s_nop 0
	v_cvt_pk_bf16_f32 v67, v68, v69
	global_store_dwordx4 v[80:81], v[64:67], off
	s_nop 1
	v_pk_mul_f32 v[66:67], v[50:51], v[148:149] op_sel_hi:[1,0]
	v_pk_mul_f32 v[50:51], v[48:49], v[148:149] op_sel_hi:[1,0]
	v_mul_f32_e32 v48, 0xbfb8aa3b, v60
	v_mul_f32_e32 v49, 0xbfb8aa3b, v61
	v_exp_f32_e32 v48, v48
	v_exp_f32_e32 v49, v49
	v_add_u32_e32 v64, 0x80, v210
	v_mad_i64_i32 v[64:65], s[0:1], v64, s2, v[132:133]
	v_add_f32_e32 v48, 1.0, v48
	v_add_f32_e32 v49, 1.0, v49
	v_rcp_f32_e32 v48, v48
	v_rcp_f32_e32 v49, v49
	v_lshl_add_u64 v[64:65], v[64:65], 0, v[134:135]
	v_pk_mul_f32 v[48:49], v[60:61], v[48:49]
	s_nop 0
	v_pk_mul_f32 v[48:49], v[52:53], v[48:49]
	s_nop 0
	v_cvt_pk_bf16_f32 v48, v48, v49
	v_mul_f32_e32 v49, 0xbfb8aa3b, v62
	v_exp_f32_e32 v49, v49
	s_nop 0
	v_add_f32_e32 v49, 1.0, v49
	v_rcp_f32_e32 v52, v49
	v_mul_f32_e32 v49, 0xbfb8aa3b, v63
	v_exp_f32_e32 v49, v49
	s_nop 0
	v_add_f32_e32 v49, 1.0, v49
	v_rcp_f32_e32 v53, v49
	s_nop 0
	v_pk_mul_f32 v[52:53], v[62:63], v[52:53]
	s_nop 0
	v_pk_mul_f32 v[52:53], v[54:55], v[52:53]
	s_nop 0
; __device__ __forceinline__ unsigned pk_bf16(float lo, float hi) { f32x2e v = {lo, hi}; bf16x2e b = __builtin_convertvector(v, bf16x2e); return __builtin_bit_cast(unsigned, b); }
; __device__ __forceinline__ float silu_mul(float g, float u) { return g * __builtin_amdgcn_rcpf(1.0f + __builtin_amdgcn_exp2f(-1.4426950408889634f * g)) * u; }
;     __device__ __forceinline__ void operator()(const f32x4 (&acc)[2][2][4][2], const Unit& u, int wr, int wc, int fr, int fq) const {
;     ...
;             for (int m = 0; m < 4; ++m) { bf16_t* rowp = O + (size_t)(row0 + ai * HALF + m * 16) * ldc + col0;
;                 const float rs = rsa[ai][m];
;                 const f32x4 g0 = acc[ai][0][m][0] * rs, g1 = acc[ai][0][m][1] * rs, u0 = acc[ai][1][m][0] * rs, u1 = acc[ai][1][m][1] * rs;
;                 u32x4 w; w.x = pk_bf16(silu_mul(g0[0], u0[0]), silu_mul(g0[1], u0[1])); w.y = pk_bf16(silu_mul(g0[2], u0[2]), silu_mul(g0[3], u0[3]));
;                 w.z = pk_bf16(silu_mul(g1[0], u1[0]), silu_mul(g1[1], u1[1])); w.w = pk_bf16(silu_mul(g1[2], u1[2]), silu_mul(g1[3], u1[3]));
;                 *(u32x4*)rowp = w; }
	v_cvt_pk_bf16_f32 v49, v52, v53
	v_mul_f32_e32 v52, 0xbfb8aa3b, v56
	v_mul_f32_e32 v53, 0xbfb8aa3b, v57
	v_exp_f32_e32 v52, v52
	v_exp_f32_e32 v53, v53
	v_add_f32_e32 v52, 1.0, v52
	v_add_f32_e32 v53, 1.0, v53
	v_rcp_f32_e32 v52, v52
	v_rcp_f32_e32 v53, v53
	s_nop 0
	v_pk_mul_f32 v[52:53], v[56:57], v[52:53]
	s_nop 0
	v_pk_mul_f32 v[50:51], v[50:51], v[52:53]
	s_nop 0
	v_cvt_pk_bf16_f32 v50, v50, v51
	v_mul_f32_e32 v51, 0xbfb8aa3b, v58
	v_exp_f32_e32 v51, v51
	s_nop 0
	v_add_f32_e32 v51, 1.0, v51
	v_rcp_f32_e32 v52, v51
	v_mul_f32_e32 v51, 0xbfb8aa3b, v59
	v_exp_f32_e32 v51, v51
	s_nop 0
	v_add_f32_e32 v51, 1.0, v51
	v_rcp_f32_e32 v53, v51
	s_nop 0
	v_pk_mul_f32 v[52:53], v[58:59], v[52:53]
	s_nop 0
	v_pk_mul_f32 v[52:53], v[66:67], v[52:53]
	s_nop 0
	v_cvt_pk_bf16_f32 v51, v52, v53
	global_store_dwordx4 v[64:65], v[48:51], off
	s_nop 1
	v_pk_mul_f32 v[50:51], v[34:35], v[146:147] op_sel_hi:[1,0]
	v_pk_mul_f32 v[34:35], v[32:33], v[146:147] op_sel_hi:[1,0]
	v_mul_f32_e32 v32, 0xbfb8aa3b, v44
	v_mul_f32_e32 v33, 0xbfb8aa3b, v45
	v_exp_f32_e32 v32, v32
	v_exp_f32_e32 v33, v33
	v_add_u32_e32 v48, 0x90, v210
	v_mad_i64_i32 v[48:49], s[0:1], v48, s2, v[132:133]
	v_add_f32_e32 v32, 1.0, v32
	v_add_f32_e32 v33, 1.0, v33
	v_rcp_f32_e32 v32, v32
	v_rcp_f32_e32 v33, v33
	v_lshl_add_u64 v[48:49], v[48:49], 0, v[134:135]
	v_pk_mul_f32 v[32:33], v[44:45], v[32:33]
	s_nop 0
	v_pk_mul_f32 v[32:33], v[36:37], v[32:33]
	s_nop 0
	v_cvt_pk_bf16_f32 v32, v32, v33
	v_mul_f32_e32 v33, 0xbfb8aa3b, v46
	v_exp_f32_e32 v33, v33
	s_nop 0
	v_add_f32_e32 v33, 1.0, v33
	v_rcp_f32_e32 v36, v33
	v_mul_f32_e32 v33, 0xbfb8aa3b, v47
	v_exp_f32_e32 v33, v33
	s_nop 0
	v_add_f32_e32 v33, 1.0, v33
	v_rcp_f32_e32 v37, v33
	s_nop 0
	v_pk_mul_f32 v[36:37], v[46:47], v[36:37]
	s_nop 0
	v_pk_mul_f32 v[36:37], v[38:39], v[36:37]
	s_nop 0
	v_cvt_pk_bf16_f32 v33, v36, v37
	v_mul_f32_e32 v36, 0xbfb8aa3b, v40
	v_mul_f32_e32 v37, 0xbfb8aa3b, v41
	v_exp_f32_e32 v36, v36
	v_exp_f32_e32 v37, v37
	v_add_f32_e32 v36, 1.0, v36
	v_add_f32_e32 v37, 1.0, v37
	v_rcp_f32_e32 v36, v36
	v_rcp_f32_e32 v37, v37
	s_nop 0
	v_pk_mul_f32 v[36:37], v[40:41], v[36:37]
	s_nop 0
	v_pk_mul_f32 v[34:35], v[34:35], v[36:37]
	s_nop 0
	v_cvt_pk_bf16_f32 v34, v34, v35
	v_mul_f32_e32 v35, 0xbfb8aa3b, v42
	v_exp_f32_e32 v35, v35
	s_nop 0
	v_add_f32_e32 v35, 1.0, v35
	v_rcp_f32_e32 v36, v35
	v_mul_f32_e32 v35, 0xbfb8aa3b, v43
	v_exp_f32_e32 v35, v35
	s_nop 0
	v_add_f32_e32 v35, 1.0, v35
	v_rcp_f32_e32 v37, v35
	s_nop 0
	v_pk_mul_f32 v[36:37], v[42:43], v[36:37]
	s_nop 0
	v_pk_mul_f32 v[36:37], v[50:51], v[36:37]
	s_nop 0
	v_cvt_pk_bf16_f32 v35, v36, v37
	global_store_dwordx4 v[48:49], v[32:35], off
	s_nop 1
	v_pk_mul_f32 v[34:35], v[18:19], v[136:137] op_sel_hi:[1,0]
	v_pk_mul_f32 v[18:19], v[16:17], v[136:137] op_sel_hi:[1,0]
	v_mul_f32_e32 v16, 0xbfb8aa3b, v28
	v_mul_f32_e32 v17, 0xbfb8aa3b, v29
	v_exp_f32_e32 v16, v16
	v_exp_f32_e32 v17, v17
	v_add_u32_e32 v32, 0xa0, v210
	v_mad_i64_i32 v[32:33], s[0:1], v32, s2, v[132:133]
	v_add_f32_e32 v16, 1.0, v16
	v_add_f32_e32 v17, 1.0, v17
	v_rcp_f32_e32 v16, v16
	v_rcp_f32_e32 v17, v17
	v_lshl_add_u64 v[32:33], v[32:33], 0, v[134:135]
	v_pk_mul_f32 v[16:17], v[28:29], v[16:17]
	s_nop 0
	v_pk_mul_f32 v[16:17], v[20:21], v[16:17]
	s_nop 0
	v_cvt_pk_bf16_f32 v16, v16, v17
	v_mul_f32_e32 v17, 0xbfb8aa3b, v30
	v_exp_f32_e32 v17, v17
	s_nop 0
	v_add_f32_e32 v17, 1.0, v17
	v_rcp_f32_e32 v20, v17
	v_mul_f32_e32 v17, 0xbfb8aa3b, v31
	v_exp_f32_e32 v17, v17
	s_nop 0
	v_add_f32_e32 v17, 1.0, v17
	v_rcp_f32_e32 v21, v17
	s_nop 0
	v_pk_mul_f32 v[20:21], v[30:31], v[20:21]
	s_nop 0
	v_pk_mul_f32 v[20:21], v[22:23], v[20:21]
	s_nop 0
	v_cvt_pk_bf16_f32 v17, v20, v21
	v_mul_f32_e32 v20, 0xbfb8aa3b, v24
	v_mul_f32_e32 v21, 0xbfb8aa3b, v25
	v_exp_f32_e32 v20, v20
	v_exp_f32_e32 v21, v21
	v_add_f32_e32 v20, 1.0, v20
	v_add_f32_e32 v21, 1.0, v21
	v_rcp_f32_e32 v20, v20
	v_rcp_f32_e32 v21, v21
	s_nop 0
	v_pk_mul_f32 v[20:21], v[24:25], v[20:21]
	s_nop 0
	v_pk_mul_f32 v[18:19], v[18:19], v[20:21]
	s_nop 0
	v_cvt_pk_bf16_f32 v18, v18, v19
	v_mul_f32_e32 v19, 0xbfb8aa3b, v26
	v_exp_f32_e32 v19, v19
	s_nop 0
	v_add_f32_e32 v19, 1.0, v19
	v_rcp_f32_e32 v20, v19
	v_mul_f32_e32 v19, 0xbfb8aa3b, v27
	v_exp_f32_e32 v19, v19
	s_nop 0
	v_add_f32_e32 v19, 1.0, v19
	v_rcp_f32_e32 v21, v19
	s_nop 0
	v_pk_mul_f32 v[20:21], v[26:27], v[20:21]
	s_nop 0
	v_pk_mul_f32 v[20:21], v[34:35], v[20:21]
	s_nop 0
	v_cvt_pk_bf16_f32 v19, v20, v21
	global_store_dwordx4 v[32:33], v[16:19], off
	s_nop 1
	v_pk_mul_f32 v[18:19], v[2:3], v[130:131] op_sel_hi:[1,0]
	v_pk_mul_f32 v[2:3], v[0:1], v[130:131] op_sel_hi:[1,0]
	v_mul_f32_e32 v0, 0xbfb8aa3b, v12
	v_mul_f32_e32 v1, 0xbfb8aa3b, v13
	v_exp_f32_e32 v0, v0
	v_exp_f32_e32 v1, v1
	v_add_u32_e32 v16, 0xb0, v210
	v_mad_i64_i32 v[16:17], s[0:1], v16, s2, v[132:133]
	v_add_f32_e32 v0, 1.0, v0
	v_add_f32_e32 v1, 1.0, v1
	v_rcp_f32_e32 v0, v0
	v_rcp_f32_e32 v1, v1
	v_lshl_add_u64 v[16:17], v[16:17], 0, v[134:135]
	s_mov_b64 s[0:1], -1
	v_pk_mul_f32 v[0:1], v[12:13], v[0:1]
	s_nop 0
	v_pk_mul_f32 v[0:1], v[4:5], v[0:1]
	s_nop 0
	v_cvt_pk_bf16_f32 v0, v0, v1
	v_mul_f32_e32 v1, 0xbfb8aa3b, v14
	v_exp_f32_e32 v1, v1
	s_nop 0
	v_add_f32_e32 v1, 1.0, v1
	v_rcp_f32_e32 v4, v1
	v_mul_f32_e32 v1, 0xbfb8aa3b, v15
	v_exp_f32_e32 v1, v1
	s_nop 0
	v_add_f32_e32 v1, 1.0, v1
	v_rcp_f32_e32 v5, v1
	s_nop 0
	v_pk_mul_f32 v[4:5], v[14:15], v[4:5]
	s_nop 0
	v_pk_mul_f32 v[4:5], v[6:7], v[4:5]
	s_nop 0
	v_cvt_pk_bf16_f32 v1, v4, v5
	v_mul_f32_e32 v4, 0xbfb8aa3b, v8
	v_mul_f32_e32 v5, 0xbfb8aa3b, v9
	v_exp_f32_e32 v4, v4
	v_exp_f32_e32 v5, v5
	v_add_f32_e32 v4, 1.0, v4
	v_add_f32_e32 v5, 1.0, v5
	v_rcp_f32_e32 v4, v4
	v_rcp_f32_e32 v5, v5
	s_nop 0
	v_pk_mul_f32 v[4:5], v[8:9], v[4:5]
	s_nop 0
	v_pk_mul_f32 v[2:3], v[2:3], v[4:5]
	s_nop 0
	v_cvt_pk_bf16_f32 v2, v2, v3
	v_mul_f32_e32 v3, 0xbfb8aa3b, v10
	v_exp_f32_e32 v3, v3
	s_nop 0
	v_add_f32_e32 v3, 1.0, v3
	v_rcp_f32_e32 v4, v3
	v_mul_f32_e32 v3, 0xbfb8aa3b, v11
	v_exp_f32_e32 v3, v3
	s_nop 0
	v_add_f32_e32 v3, 1.0, v3
	v_rcp_f32_e32 v5, v3
	s_nop 0
	v_pk_mul_f32 v[4:5], v[10:11], v[4:5]
	s_nop 0
	v_pk_mul_f32 v[4:5], v[18:19], v[4:5]
	s_nop 0
	v_cvt_pk_bf16_f32 v3, v4, v5
	global_store_dwordx4 v[16:17], v[0:3], off
; __device__ __forceinline__ unsigned pk_bf16(float lo, float hi) { f32x2e v = {lo, hi}; bf16x2e b = __builtin_convertvector(v, bf16x2e); return __builtin_bit_cast(unsigned, b); }
; __device__ __forceinline__ float silu_mul(float g, float u) { return g * __builtin_amdgcn_rcpf(1.0f + __builtin_amdgcn_exp2f(-1.4426950408889634f * g)) * u; }
; #define PG8_BAR __builtin_amdgcn_s_barrier()
;     __device__ __forceinline__ void operator()(const f32x4 (&acc)[2][2][4][2], const Unit& u, int wr, int wc, int fr, int fq) const {
;     ...
;             for (int m = 0; m < 4; ++m) { bf16_t* rowp = O + (size_t)(row0 + ai * HALF + m * 16) * ldc + col0;
;                 const float rs = rsa[ai][m];
;                 const f32x4 g0 = acc[ai][0][m][0] * rs, g1 = acc[ai][0][m][1] * rs, u0 = acc[ai][1][m][0] * rs, u1 = acc[ai][1][m][1] * rs;
;                 u32x4 w; w.x = pk_bf16(silu_mul(g0[0], u0[0]), silu_mul(g0[1], u0[1])); w.y = pk_bf16(silu_mul(g0[2], u0[2]), silu_mul(g0[3], u0[3]));
;                 w.z = pk_bf16(silu_mul(g1[0], u1[0]), silu_mul(g1[1], u1[1])); w.w = pk_bf16(silu_mul(g1[2], u1[2]), silu_mul(g1[3], u1[3]));
;                 *(u32x4*)rowp = w; }
; template <class Epi, class Sched, bool ALIGN_EPI = false, bool SP2 = false>
; __device__ __forceinline__ void gemm_phase(PG8_LAS unsigned char* lds, const Gemm g, const Sched& S, const Epi& E) {
;     ...
;         if (!has_next) break;
; #pragma unroll
;         for (int a = 0; a < 2; ++a)
; #pragma unroll
;             for (int b = 0; b < 2; ++b)
; #pragma unroll
;                 for (int m = 0; m < 4; ++m)
; #pragma unroll
;                     for (int n = 0; n < 2; ++n) acc[a][b][m][n] = (f32x4){0.f, 0.f, 0.f, 0.f};
;         cur = nxt; cA = nA; cB = nB; ++ui;
;         if constexpr (ALIGN_EPI) { if (wr == 1) PG8_BAR; }
;     }
.Lswi_join:
	s_cbranch_vccnz .LBB0_413
	s_andn2_b64 vcc, exec, s[10:11]
	s_cbranch_vccnz .LBB0_412
	s_barrier
	s_branch .LBB0_412
.Lswi_hit:
	v_lshrrev_b32_e32 v236, 6, v216
	v_and_b32_e32 v237, 15, v216
	v_lshlrev_b32_e32 v236, 9, v236
	v_lshl_add_u32 v236, v237, 5, v236
	v_add_u32_e32 v236, 0x21000, v236
	v_mov_b32_e32 v237, s6
	v_add_u32_e32 v237, 1, v237
	s_lshl_b32 s0, s6, 8
	s_add_i32 s0, s0, s73
	v_or_b32_e32 v130, s0, v206
	v_ashrrev_i32_e32 v131, 31, v130
	v_lshlrev_b64 v[132:133], 7, v[130:131]
	v_lshl_add_u64 v[132:133], v[184:185], 0, v[132:133]
	v_or_b32_e32 v132, 16, v130
	v_ashrrev_i32_e32 v133, 31, v132
	v_lshlrev_b64 v[132:133], 7, v[132:133]
	v_lshl_add_u64 v[132:133], v[184:185], 0, v[132:133]
	v_or_b32_e32 v132, 32, v130
	v_ashrrev_i32_e32 v133, 31, v132
	v_lshlrev_b64 v[132:133], 7, v[132:133]
	v_lshl_add_u64 v[132:133], v[184:185], 0, v[132:133]
	v_or_b32_e32 v132, 48, v130
	v_ashrrev_i32_e32 v133, 31, v132
	v_lshlrev_b64 v[132:133], 7, v[132:133]
	v_lshl_add_u64 v[132:133], v[184:185], 0, v[132:133]
	v_add_u32_e32 v132, 0x80, v130
	v_ashrrev_i32_e32 v133, 31, v132
	v_lshlrev_b64 v[132:133], 7, v[132:133]
	v_lshl_add_u64 v[132:133], v[184:185], 0, v[132:133]
	v_add_u32_e32 v132, 0x90, v130
	v_ashrrev_i32_e32 v133, 31, v132
	v_lshlrev_b64 v[132:133], 7, v[132:133]
	v_lshl_add_u64 v[132:133], v[184:185], 0, v[132:133]
	v_add_u32_e32 v132, 0xa0, v130
	v_ashrrev_i32_e32 v133, 31, v132
	v_lshlrev_b64 v[132:133], 7, v[132:133]
	v_add_u32_e32 v130, 0xb0, v130
	v_lshl_add_u64 v[132:133], v[184:185], 0, v[132:133]
	v_ashrrev_i32_e32 v131, 31, v130
	v_lshlrev_b64 v[130:131], 7, v[130:131]
	v_lshl_add_u64 v[130:131], v[184:185], 0, v[130:131]
	s_nop 0
	v_and_b32_e32 v192, 64, v220
	v_xor_b32_e32 v191, 1, v220
	v_add_u32_e32 v192, 64, v192
	v_cmp_lt_i32_e32 vcc, v191, v192
	v_or_b32_e32 v210, s0, v193
	v_readlane_b32 s0, v254, 63
	v_cndmask_b32_e32 v191, v220, v191, vcc
	v_lshlrev_b32_e32 v212, 2, v191
	v_xor_b32_e32 v191, 2, v220
	v_cmp_lt_i32_e32 vcc, v191, v192
	v_lshl_or_b32 v190, s2, 7, v208
	v_readlane_b32 s1, v255, 0
	v_cndmask_b32_e32 v191, v220, v191, vcc
	v_lshlrev_b32_e32 v211, 2, v191
	v_lshlrev_b32_e32 v191, 2, v220
	v_and_or_b32 v191, v191, s25, v207
	s_movk_i32 s2, 0x2c00
	s_waitcnt vmcnt(0) lgkmcnt(0)
	s_nop 0
	s_nop 0
	s_waitcnt lgkmcnt(0)
	s_waitcnt lgkmcnt(0)
	v_mov_b64_e32 v[204:205], s[24:25]
	s_nop 0
	s_nop 0
	ds_read_b32 v202, v236
	s_waitcnt lgkmcnt(0)
	v_pk_mul_f32 v[126:127], v[126:127], v[202:203] op_sel_hi:[1,0]
	v_pk_mul_f32 v[118:119], v[118:119], v[202:203] op_sel_hi:[1,0]
	v_pk_mul_f32 v[140:141], v[116:117], v[202:203] op_sel_hi:[1,0]
	v_pk_mul_f32 v[116:117], v[114:115], v[202:203] op_sel_hi:[1,0]
	v_mul_f32_e32 v114, 0xbfb8aa3b, v126
	v_mul_f32_e32 v115, 0xbfb8aa3b, v127
	v_exp_f32_e32 v114, v114
	v_exp_f32_e32 v115, v115
	v_pk_mul_f32 v[128:129], v[128:129], v[202:203] op_sel_hi:[1,0]
	v_add_f32_e32 v114, 1.0, v114
	v_add_f32_e32 v115, 1.0, v115
	v_rcp_f32_e32 v114, v114
	v_rcp_f32_e32 v115, v115
	s_nop 0
	v_pk_mul_f32 v[114:115], v[126:127], v[114:115]
	v_pk_mul_f32 v[114:115], v[118:119], v[114:115]
	v_cvt_pk_bf16_f32 v114, v114, v115
	v_mul_f32_e32 v115, 0xbfb8aa3b, v128
	v_exp_f32_e32 v115, v115
	s_nop 0
	v_add_f32_e32 v115, 1.0, v115
	v_rcp_f32_e32 v118, v115
	v_mul_f32_e32 v115, 0xbfb8aa3b, v129
	v_exp_f32_e32 v115, v115
	s_waitcnt lgkmcnt(0)
	v_add_f32_e32 v115, 1.0, v115
	v_rcp_f32_e32 v119, v115
	s_waitcnt lgkmcnt(0)
	s_waitcnt lgkmcnt(0)
	v_pk_mul_f32 v[120:121], v[120:121], v[202:203] op_sel_hi:[1,0]
	v_pk_mul_f32 v[118:119], v[128:129], v[118:119]
	v_pk_mul_f32 v[122:123], v[122:123], v[202:203] op_sel_hi:[1,0]
	v_pk_mul_f32 v[118:119], v[120:121], v[118:119]
	v_cvt_pk_bf16_f32 v115, v118, v119
	v_mul_f32_e32 v118, 0xbfb8aa3b, v122
	v_mul_f32_e32 v119, 0xbfb8aa3b, v123
	v_exp_f32_e32 v118, v118
	v_exp_f32_e32 v119, v119
	s_waitcnt lgkmcnt(0)
	s_waitcnt lgkmcnt(0)
	v_add_f32_e32 v118, 1.0, v118
	v_add_f32_e32 v119, 1.0, v119
	ds_read_b32 v164, v236 offset:4
	v_rcp_f32_e32 v118, v118
	v_rcp_f32_e32 v119, v119
	s_waitcnt lgkmcnt(0)
	v_pk_mul_f32 v[118:119], v[122:123], v[118:119]
	v_pk_mul_f32 v[124:125], v[124:125], v[202:203] op_sel_hi:[1,0]
	v_pk_mul_f32 v[116:117], v[116:117], v[118:119]
	v_cvt_pk_bf16_f32 v116, v116, v117
	v_mul_f32_e32 v117, 0xbfb8aa3b, v124
	ds_read_b32 v148, v236 offset:8
	v_exp_f32_e32 v117, v117
	s_nop 0
	v_add_f32_e32 v117, 1.0, v117
	v_rcp_f32_e32 v118, v117
	v_mul_f32_e32 v117, 0xbfb8aa3b, v125
	v_exp_f32_e32 v117, v117
	ds_read_b32 v136, v236 offset:12
	v_add_f32_e32 v117, 1.0, v117
	v_rcp_f32_e32 v119, v117
	ds_read_b32 v192, v236 offset:16
	ds_read_b32 v162, v236 offset:20
	ds_read_b32 v146, v236 offset:24
	ds_read_b32 v130, v236 offset:28
	v_ashrrev_i32_e32 v191, 31, v190
	v_mov_b64_e32 v[132:133], s[0:1]
	v_pk_mul_f32 v[118:119], v[124:125], v[118:119]
	v_mad_i64_i32 v[138:139], s[0:1], v210, s2, v[132:133]
	v_lshlrev_b64 v[134:135], 1, v[190:191]
	v_pk_mul_f32 v[118:119], v[140:141], v[118:119]
	v_lshl_add_u64 v[138:139], v[138:139], 0, v[134:135]
	v_cvt_pk_bf16_f32 v117, v118, v119
	s_waitcnt lgkmcnt(0)
; __device__ __forceinline__ unsigned pk_bf16(float lo, float hi) { f32x2e v = {lo, hi}; bf16x2e b = __builtin_convertvector(v, bf16x2e); return __builtin_bit_cast(unsigned, b); }
; __device__ __forceinline__ float silu_mul(float g, float u) { return g * __builtin_amdgcn_rcpf(1.0f + __builtin_amdgcn_exp2f(-1.4426950408889634f * g)) * u; }
;     __device__ __forceinline__ void operator()(const f32x4 (&acc)[2][2][4][2], const Unit& u, int wr, int wc, int fr, int fq) const {
;     ...
;             for (int m = 0; m < 4; ++m) { bf16_t* rowp = O + (size_t)(row0 + ai * HALF + m * 16) * ldc + col0;
;                 const float rs = rsa[ai][m];
;                 const f32x4 g0 = acc[ai][0][m][0] * rs, g1 = acc[ai][0][m][1] * rs, u0 = acc[ai][1][m][0] * rs, u1 = acc[ai][1][m][1] * rs;
;                 u32x4 w; w.x = pk_bf16(silu_mul(g0[0], u0[0]), silu_mul(g0[1], u0[1])); w.y = pk_bf16(silu_mul(g0[2], u0[2]), silu_mul(g0[3], u0[3]));
;                 w.z = pk_bf16(silu_mul(g1[0], u1[0]), silu_mul(g1[1], u1[1])); w.w = pk_bf16(silu_mul(g1[2], u1[2]), silu_mul(g1[3], u1[3]));
;                 *(u32x4*)rowp = w; }
	v_pk_mul_f32 v[110:111], v[110:111], v[192:193] op_sel_hi:[1,0]
	global_store_dwordx4 v[138:139], v[114:117], off
	v_pk_mul_f32 v[102:103], v[102:103], v[192:193] op_sel_hi:[1,0]
	v_pk_mul_f32 v[112:113], v[112:113], v[192:193] op_sel_hi:[1,0]
	v_pk_mul_f32 v[116:117], v[100:101], v[192:193] op_sel_hi:[1,0]
	v_pk_mul_f32 v[100:101], v[98:99], v[192:193] op_sel_hi:[1,0]
	v_mul_f32_e32 v98, 0xbfb8aa3b, v110
	v_mul_f32_e32 v99, 0xbfb8aa3b, v111
	v_exp_f32_e32 v98, v98
	v_exp_f32_e32 v99, v99
	v_pk_mul_f32 v[104:105], v[104:105], v[192:193] op_sel_hi:[1,0]
	v_pk_mul_f32 v[106:107], v[106:107], v[192:193] op_sel_hi:[1,0]
	v_add_f32_e32 v98, 1.0, v98
	v_add_f32_e32 v99, 1.0, v99
	v_rcp_f32_e32 v98, v98
	v_rcp_f32_e32 v99, v99
	v_pk_mul_f32 v[108:109], v[108:109], v[192:193] op_sel_hi:[1,0]
	v_or_b32_e32 v114, 16, v210
	v_mad_i64_i32 v[114:115], s[0:1], v114, s2, v[132:133]
	v_pk_mul_f32 v[98:99], v[110:111], v[98:99]
	v_lshl_add_u64 v[114:115], v[114:115], 0, v[134:135]
	v_pk_mul_f32 v[98:99], v[102:103], v[98:99]
	v_pk_mul_f32 v[92:93], v[92:93], v[164:165] op_sel_hi:[1,0]
	v_cvt_pk_bf16_f32 v98, v98, v99
	v_mul_f32_e32 v99, 0xbfb8aa3b, v112
	v_exp_f32_e32 v99, v99
	v_pk_mul_f32 v[84:85], v[84:85], v[164:165] op_sel_hi:[1,0]
	v_pk_mul_f32 v[94:95], v[94:95], v[164:165] op_sel_hi:[1,0]
	v_pk_mul_f32 v[86:87], v[86:87], v[164:165] op_sel_hi:[1,0]
	v_add_f32_e32 v99, 1.0, v99
	v_rcp_f32_e32 v102, v99
	v_mul_f32_e32 v99, 0xbfb8aa3b, v113
	v_exp_f32_e32 v99, v99
	v_pk_mul_f32 v[88:89], v[88:89], v[164:165] op_sel_hi:[1,0]
	v_pk_mul_f32 v[90:91], v[90:91], v[164:165] op_sel_hi:[1,0]
	s_waitcnt lgkmcnt(0)
	v_pk_mul_f32 v[76:77], v[76:77], v[162:163] op_sel_hi:[1,0]
	v_add_f32_e32 v99, 1.0, v99
	v_rcp_f32_e32 v103, v99
	v_pk_mul_f32 v[68:69], v[68:69], v[162:163] op_sel_hi:[1,0]
	v_pk_mul_f32 v[78:79], v[78:79], v[162:163] op_sel_hi:[1,0]
	v_pk_mul_f32 v[70:71], v[70:71], v[162:163] op_sel_hi:[1,0]
	v_pk_mul_f32 v[102:103], v[112:113], v[102:103]
	v_pk_mul_f32 v[72:73], v[72:73], v[162:163] op_sel_hi:[1,0]
	v_pk_mul_f32 v[102:103], v[104:105], v[102:103]
	v_pk_mul_f32 v[74:75], v[74:75], v[162:163] op_sel_hi:[1,0]
	v_cvt_pk_bf16_f32 v99, v102, v103
	v_mul_f32_e32 v102, 0xbfb8aa3b, v106
	v_mul_f32_e32 v103, 0xbfb8aa3b, v107
	v_exp_f32_e32 v102, v102
	v_exp_f32_e32 v103, v103
	v_pk_mul_f32 v[60:61], v[60:61], v[148:149] op_sel_hi:[1,0]
	v_pk_mul_f32 v[52:53], v[52:53], v[148:149] op_sel_hi:[1,0]
	v_add_f32_e32 v102, 1.0, v102
	v_add_f32_e32 v103, 1.0, v103
	v_rcp_f32_e32 v102, v102
	v_rcp_f32_e32 v103, v103
	v_pk_mul_f32 v[62:63], v[62:63], v[148:149] op_sel_hi:[1,0]
	v_pk_mul_f32 v[54:55], v[54:55], v[148:149] op_sel_hi:[1,0]
	v_pk_mul_f32 v[56:57], v[56:57], v[148:149] op_sel_hi:[1,0]
	v_pk_mul_f32 v[102:103], v[106:107], v[102:103]
	v_pk_mul_f32 v[58:59], v[58:59], v[148:149] op_sel_hi:[1,0]
	v_pk_mul_f32 v[100:101], v[100:101], v[102:103]
	v_pk_mul_f32 v[44:45], v[44:45], v[146:147] op_sel_hi:[1,0]
	v_cvt_pk_bf16_f32 v100, v100, v101
	v_mul_f32_e32 v101, 0xbfb8aa3b, v108
	v_exp_f32_e32 v101, v101
	v_pk_mul_f32 v[36:37], v[36:37], v[146:147] op_sel_hi:[1,0]
	v_pk_mul_f32 v[46:47], v[46:47], v[146:147] op_sel_hi:[1,0]
	v_pk_mul_f32 v[38:39], v[38:39], v[146:147] op_sel_hi:[1,0]
	v_add_f32_e32 v101, 1.0, v101
	v_rcp_f32_e32 v102, v101
	v_mul_f32_e32 v101, 0xbfb8aa3b, v109
	v_exp_f32_e32 v101, v101
	v_pk_mul_f32 v[40:41], v[40:41], v[146:147] op_sel_hi:[1,0]
	v_pk_mul_f32 v[42:43], v[42:43], v[146:147] op_sel_hi:[1,0]
	v_pk_mul_f32 v[28:29], v[28:29], v[136:137] op_sel_hi:[1,0]
	v_add_f32_e32 v101, 1.0, v101
	v_rcp_f32_e32 v103, v101
	v_pk_mul_f32 v[20:21], v[20:21], v[136:137] op_sel_hi:[1,0]
	v_pk_mul_f32 v[30:31], v[30:31], v[136:137] op_sel_hi:[1,0]
	v_pk_mul_f32 v[22:23], v[22:23], v[136:137] op_sel_hi:[1,0]
	v_pk_mul_f32 v[102:103], v[108:109], v[102:103]
	v_pk_mul_f32 v[24:25], v[24:25], v[136:137] op_sel_hi:[1,0]
	v_pk_mul_f32 v[102:103], v[116:117], v[102:103]
	v_pk_mul_f32 v[26:27], v[26:27], v[136:137] op_sel_hi:[1,0]
	v_cvt_pk_bf16_f32 v101, v102, v103
	global_store_dwordx4 v[114:115], v[98:101], off
	v_pk_mul_f32 v[12:13], v[12:13], v[130:131] op_sel_hi:[1,0]
	v_pk_mul_f32 v[4:5], v[4:5], v[130:131] op_sel_hi:[1,0]
	v_pk_mul_f32 v[100:101], v[82:83], v[164:165] op_sel_hi:[1,0]
	v_pk_mul_f32 v[82:83], v[80:81], v[164:165] op_sel_hi:[1,0]
	v_mul_f32_e32 v80, 0xbfb8aa3b, v92
	v_mul_f32_e32 v81, 0xbfb8aa3b, v93
	v_exp_f32_e32 v80, v80
	v_exp_f32_e32 v81, v81
	v_or_b32_e32 v98, 32, v210
	v_mad_i64_i32 v[98:99], s[0:1], v98, s2, v[132:133]
	v_add_f32_e32 v80, 1.0, v80
	v_add_f32_e32 v81, 1.0, v81
	v_rcp_f32_e32 v80, v80
	v_rcp_f32_e32 v81, v81
	v_lshl_add_u64 v[98:99], v[98:99], 0, v[134:135]
	v_pk_mul_f32 v[14:15], v[14:15], v[130:131] op_sel_hi:[1,0]
	v_pk_mul_f32 v[6:7], v[6:7], v[130:131] op_sel_hi:[1,0]
	v_pk_mul_f32 v[80:81], v[92:93], v[80:81]
	v_pk_mul_f32 v[8:9], v[8:9], v[130:131] op_sel_hi:[1,0]
	v_pk_mul_f32 v[80:81], v[84:85], v[80:81]
	v_pk_mul_f32 v[10:11], v[10:11], v[130:131] op_sel_hi:[1,0]
	v_cvt_pk_bf16_f32 v80, v80, v81
	v_mul_f32_e32 v81, 0xbfb8aa3b, v94
	v_exp_f32_e32 v81, v81
	s_andn2_b64 vcc, exec, s[38:39]
	v_add_f32_e32 v81, 1.0, v81
	v_rcp_f32_e32 v84, v81
	v_mul_f32_e32 v81, 0xbfb8aa3b, v95
	v_exp_f32_e32 v81, v81
	s_nop 0
	v_add_f32_e32 v81, 1.0, v81
	v_rcp_f32_e32 v85, v81
	s_nop 0
	v_pk_mul_f32 v[84:85], v[94:95], v[84:85]
	s_nop 0
	v_pk_mul_f32 v[84:85], v[86:87], v[84:85]
	s_nop 0
	v_cvt_pk_bf16_f32 v81, v84, v85
	v_mul_f32_e32 v84, 0xbfb8aa3b, v88
	v_mul_f32_e32 v85, 0xbfb8aa3b, v89
	v_exp_f32_e32 v84, v84
	v_exp_f32_e32 v85, v85
	v_add_f32_e32 v84, 1.0, v84
	v_add_f32_e32 v85, 1.0, v85
	v_rcp_f32_e32 v84, v84
; __device__ __forceinline__ unsigned pk_bf16(float lo, float hi) { f32x2e v = {lo, hi}; bf16x2e b = __builtin_convertvector(v, bf16x2e); return __builtin_bit_cast(unsigned, b); }
; __device__ __forceinline__ float silu_mul(float g, float u) { return g * __builtin_amdgcn_rcpf(1.0f + __builtin_amdgcn_exp2f(-1.4426950408889634f * g)) * u; }
;     __device__ __forceinline__ void operator()(const f32x4 (&acc)[2][2][4][2], const Unit& u, int wr, int wc, int fr, int fq) const {
;     ...
;             for (int m = 0; m < 4; ++m) { bf16_t* rowp = O + (size_t)(row0 + ai * HALF + m * 16) * ldc + col0;
;                 const float rs = rsa[ai][m];
;                 const f32x4 g0 = acc[ai][0][m][0] * rs, g1 = acc[ai][0][m][1] * rs, u0 = acc[ai][1][m][0] * rs, u1 = acc[ai][1][m][1] * rs;
;                 u32x4 w; w.x = pk_bf16(silu_mul(g0[0], u0[0]), silu_mul(g0[1], u0[1])); w.y = pk_bf16(silu_mul(g0[2], u0[2]), silu_mul(g0[3], u0[3]));
;                 w.z = pk_bf16(silu_mul(g1[0], u1[0]), silu_mul(g1[1], u1[1])); w.w = pk_bf16(silu_mul(g1[2], u1[2]), silu_mul(g1[3], u1[3]));
;                 *(u32x4*)rowp = w; }
	v_rcp_f32_e32 v85, v85
	s_nop 0
	v_pk_mul_f32 v[84:85], v[88:89], v[84:85]
	s_nop 0
	v_pk_mul_f32 v[82:83], v[82:83], v[84:85]
	s_nop 0
	v_cvt_pk_bf16_f32 v82, v82, v83
	v_mul_f32_e32 v83, 0xbfb8aa3b, v90
	v_exp_f32_e32 v83, v83
	s_nop 0
	v_add_f32_e32 v83, 1.0, v83
	v_rcp_f32_e32 v84, v83
	v_mul_f32_e32 v83, 0xbfb8aa3b, v91
	v_exp_f32_e32 v83, v83
	s_nop 0
	v_add_f32_e32 v83, 1.0, v83
	v_rcp_f32_e32 v85, v83
	s_nop 0
	v_pk_mul_f32 v[84:85], v[90:91], v[84:85]
	s_nop 0
	v_pk_mul_f32 v[84:85], v[100:101], v[84:85]
	s_nop 0
	v_cvt_pk_bf16_f32 v83, v84, v85
	global_store_dwordx4 v[98:99], v[80:83], off
	s_nop 1
	v_pk_mul_f32 v[82:83], v[66:67], v[162:163] op_sel_hi:[1,0]
	v_pk_mul_f32 v[66:67], v[64:65], v[162:163] op_sel_hi:[1,0]
	v_mul_f32_e32 v64, 0xbfb8aa3b, v76
	v_mul_f32_e32 v65, 0xbfb8aa3b, v77
	v_exp_f32_e32 v64, v64
	v_exp_f32_e32 v65, v65
	v_or_b32_e32 v80, 48, v210
	v_mad_i64_i32 v[80:81], s[0:1], v80, s2, v[132:133]
	v_add_f32_e32 v64, 1.0, v64
	v_add_f32_e32 v65, 1.0, v65
	v_rcp_f32_e32 v64, v64
	v_rcp_f32_e32 v65, v65
	v_lshl_add_u64 v[80:81], v[80:81], 0, v[134:135]
	v_pk_mul_f32 v[64:65], v[76:77], v[64:65]
	s_nop 0
	v_pk_mul_f32 v[64:65], v[68:69], v[64:65]
	s_nop 0
	v_cvt_pk_bf16_f32 v64, v64, v65
	v_mul_f32_e32 v65, 0xbfb8aa3b, v78
	v_exp_f32_e32 v65, v65
	s_nop 0
	v_add_f32_e32 v65, 1.0, v65
	v_rcp_f32_e32 v68, v65
	v_mul_f32_e32 v65, 0xbfb8aa3b, v79
	v_exp_f32_e32 v65, v65
	s_nop 0
	v_add_f32_e32 v65, 1.0, v65
	v_rcp_f32_e32 v69, v65
	s_nop 0
	v_pk_mul_f32 v[68:69], v[78:79], v[68:69]
	s_nop 0
	v_pk_mul_f32 v[68:69], v[70:71], v[68:69]
	s_nop 0
	v_cvt_pk_bf16_f32 v65, v68, v69
	v_mul_f32_e32 v68, 0xbfb8aa3b, v72
	v_mul_f32_e32 v69, 0xbfb8aa3b, v73
	v_exp_f32_e32 v68, v68
	v_exp_f32_e32 v69, v69
	v_add_f32_e32 v68, 1.0, v68
	v_add_f32_e32 v69, 1.0, v69
	v_rcp_f32_e32 v68, v68
	v_rcp_f32_e32 v69, v69
	s_nop 0
	v_pk_mul_f32 v[68:69], v[72:73], v[68:69]
	s_nop 0
	v_pk_mul_f32 v[66:67], v[66:67], v[68:69]
	s_nop 0
	v_cvt_pk_bf16_f32 v66, v66, v67
	v_mul_f32_e32 v67, 0xbfb8aa3b, v74
	v_exp_f32_e32 v67, v67
	s_nop 0
	v_add_f32_e32 v67, 1.0, v67
	v_rcp_f32_e32 v68, v67
	v_mul_f32_e32 v67, 0xbfb8aa3b, v75
	v_exp_f32_e32 v67, v67
	s_nop 0
	v_add_f32_e32 v67, 1.0, v67
	v_rcp_f32_e32 v69, v67
	s_nop 0
	v_pk_mul_f32 v[68:69], v[74:75], v[68:69]
	s_nop 0
	v_pk_mul_f32 v[68:69], v[82:83], v[68:69]
	s_nop 0
	v_cvt_pk_bf16_f32 v67, v68, v69
	global_store_dwordx4 v[80:81], v[64:67], off
	s_nop 1
	v_pk_mul_f32 v[66:67], v[50:51], v[148:149] op_sel_hi:[1,0]
	v_pk_mul_f32 v[50:51], v[48:49], v[148:149] op_sel_hi:[1,0]
	v_mul_f32_e32 v48, 0xbfb8aa3b, v60
	v_mul_f32_e32 v49, 0xbfb8aa3b, v61
	v_exp_f32_e32 v48, v48
	v_exp_f32_e32 v49, v49
	v_add_u32_e32 v64, 0x80, v210
	v_mad_i64_i32 v[64:65], s[0:1], v64, s2, v[132:133]
	v_add_f32_e32 v48, 1.0, v48
	v_add_f32_e32 v49, 1.0, v49
	v_rcp_f32_e32 v48, v48
	v_rcp_f32_e32 v49, v49
	v_lshl_add_u64 v[64:65], v[64:65], 0, v[134:135]
	v_pk_mul_f32 v[48:49], v[60:61], v[48:49]
	s_nop 0
	v_pk_mul_f32 v[48:49], v[52:53], v[48:49]
	s_nop 0
	v_cvt_pk_bf16_f32 v48, v48, v49
	v_mul_f32_e32 v49, 0xbfb8aa3b, v62
	v_exp_f32_e32 v49, v49
	s_nop 0
	v_add_f32_e32 v49, 1.0, v49
	v_rcp_f32_e32 v52, v49
	v_mul_f32_e32 v49, 0xbfb8aa3b, v63
	v_exp_f32_e32 v49, v49
	s_nop 0
	v_add_f32_e32 v49, 1.0, v49
	v_rcp_f32_e32 v53, v49
	s_nop 0
	v_pk_mul_f32 v[52:53], v[62:63], v[52:53]
	s_nop 0
	v_pk_mul_f32 v[52:53], v[54:55], v[52:53]
	s_nop 0
	v_cvt_pk_bf16_f32 v49, v52, v53
	v_mul_f32_e32 v52, 0xbfb8aa3b, v56
	v_mul_f32_e32 v53, 0xbfb8aa3b, v57
	v_exp_f32_e32 v52, v52
	v_exp_f32_e32 v53, v53
	v_add_f32_e32 v52, 1.0, v52
	v_add_f32_e32 v53, 1.0, v53
	v_rcp_f32_e32 v52, v52
	v_rcp_f32_e32 v53, v53
	s_nop 0
	v_pk_mul_f32 v[52:53], v[56:57], v[52:53]
	s_nop 0
	v_pk_mul_f32 v[50:51], v[50:51], v[52:53]
	s_nop 0
	v_cvt_pk_bf16_f32 v50, v50, v51
	v_mul_f32_e32 v51, 0xbfb8aa3b, v58
	v_exp_f32_e32 v51, v51
	s_nop 0
	v_add_f32_e32 v51, 1.0, v51
	v_rcp_f32_e32 v52, v51
	v_mul_f32_e32 v51, 0xbfb8aa3b, v59
	v_exp_f32_e32 v51, v51
	s_nop 0
	v_add_f32_e32 v51, 1.0, v51
	v_rcp_f32_e32 v53, v51
	s_nop 0
	v_pk_mul_f32 v[52:53], v[58:59], v[52:53]
	s_nop 0
	v_pk_mul_f32 v[52:53], v[66:67], v[52:53]
	s_nop 0
	v_cvt_pk_bf16_f32 v51, v52, v53
	global_store_dwordx4 v[64:65], v[48:51], off
	s_nop 1
	v_pk_mul_f32 v[50:51], v[34:35], v[146:147] op_sel_hi:[1,0]
	v_pk_mul_f32 v[34:35], v[32:33], v[146:147] op_sel_hi:[1,0]
	v_mul_f32_e32 v32, 0xbfb8aa3b, v44
	v_mul_f32_e32 v33, 0xbfb8aa3b, v45
	v_exp_f32_e32 v32, v32
	v_exp_f32_e32 v33, v33
	v_add_u32_e32 v48, 0x90, v210
	v_mad_i64_i32 v[48:49], s[0:1], v48, s2, v[132:133]
	v_add_f32_e32 v32, 1.0, v32
	v_add_f32_e32 v33, 1.0, v33
	v_rcp_f32_e32 v32, v32
	v_rcp_f32_e32 v33, v33
	v_lshl_add_u64 v[48:49], v[48:49], 0, v[134:135]
	v_pk_mul_f32 v[32:33], v[44:45], v[32:33]
	s_nop 0
	v_pk_mul_f32 v[32:33], v[36:37], v[32:33]
; __device__ __forceinline__ unsigned pk_bf16(float lo, float hi) { f32x2e v = {lo, hi}; bf16x2e b = __builtin_convertvector(v, bf16x2e); return __builtin_bit_cast(unsigned, b); }
; __device__ __forceinline__ float silu_mul(float g, float u) { return g * __builtin_amdgcn_rcpf(1.0f + __builtin_amdgcn_exp2f(-1.4426950408889634f * g)) * u; }
;     __device__ __forceinline__ void operator()(const f32x4 (&acc)[2][2][4][2], const Unit& u, int wr, int wc, int fr, int fq) const {
;     ...
;             for (int m = 0; m < 4; ++m) { bf16_t* rowp = O + (size_t)(row0 + ai * HALF + m * 16) * ldc + col0;
;                 const float rs = rsa[ai][m];
;                 const f32x4 g0 = acc[ai][0][m][0] * rs, g1 = acc[ai][0][m][1] * rs, u0 = acc[ai][1][m][0] * rs, u1 = acc[ai][1][m][1] * rs;
;                 u32x4 w; w.x = pk_bf16(silu_mul(g0[0], u0[0]), silu_mul(g0[1], u0[1])); w.y = pk_bf16(silu_mul(g0[2], u0[2]), silu_mul(g0[3], u0[3]));
;                 w.z = pk_bf16(silu_mul(g1[0], u1[0]), silu_mul(g1[1], u1[1])); w.w = pk_bf16(silu_mul(g1[2], u1[2]), silu_mul(g1[3], u1[3]));
;                 *(u32x4*)rowp = w; }
	s_nop 0
	v_cvt_pk_bf16_f32 v32, v32, v33
	v_mul_f32_e32 v33, 0xbfb8aa3b, v46
	v_exp_f32_e32 v33, v33
	s_nop 0
	v_add_f32_e32 v33, 1.0, v33
	v_rcp_f32_e32 v36, v33
	v_mul_f32_e32 v33, 0xbfb8aa3b, v47
	v_exp_f32_e32 v33, v33
	s_nop 0
	v_add_f32_e32 v33, 1.0, v33
	v_rcp_f32_e32 v37, v33
	s_nop 0
	v_pk_mul_f32 v[36:37], v[46:47], v[36:37]
	s_nop 0
	v_pk_mul_f32 v[36:37], v[38:39], v[36:37]
	s_nop 0
	v_cvt_pk_bf16_f32 v33, v36, v37
	v_mul_f32_e32 v36, 0xbfb8aa3b, v40
	v_mul_f32_e32 v37, 0xbfb8aa3b, v41
	v_exp_f32_e32 v36, v36
	v_exp_f32_e32 v37, v37
	v_add_f32_e32 v36, 1.0, v36
	v_add_f32_e32 v37, 1.0, v37
	v_rcp_f32_e32 v36, v36
	v_rcp_f32_e32 v37, v37
	s_nop 0
	v_pk_mul_f32 v[36:37], v[40:41], v[36:37]
	s_nop 0
	v_pk_mul_f32 v[34:35], v[34:35], v[36:37]
	s_nop 0
	v_cvt_pk_bf16_f32 v34, v34, v35
	v_mul_f32_e32 v35, 0xbfb8aa3b, v42
	v_exp_f32_e32 v35, v35
	s_nop 0
	v_add_f32_e32 v35, 1.0, v35
	v_rcp_f32_e32 v36, v35
	v_mul_f32_e32 v35, 0xbfb8aa3b, v43
	v_exp_f32_e32 v35, v35
	s_nop 0
	v_add_f32_e32 v35, 1.0, v35
	v_rcp_f32_e32 v37, v35
	s_nop 0
	v_pk_mul_f32 v[36:37], v[42:43], v[36:37]
	s_nop 0
	v_pk_mul_f32 v[36:37], v[50:51], v[36:37]
	s_nop 0
	v_cvt_pk_bf16_f32 v35, v36, v37
	global_store_dwordx4 v[48:49], v[32:35], off
	s_nop 1
	v_pk_mul_f32 v[34:35], v[18:19], v[136:137] op_sel_hi:[1,0]
	v_pk_mul_f32 v[18:19], v[16:17], v[136:137] op_sel_hi:[1,0]
	v_mul_f32_e32 v16, 0xbfb8aa3b, v28
	v_mul_f32_e32 v17, 0xbfb8aa3b, v29
	v_exp_f32_e32 v16, v16
	v_exp_f32_e32 v17, v17
	v_add_u32_e32 v32, 0xa0, v210
	v_mad_i64_i32 v[32:33], s[0:1], v32, s2, v[132:133]
	v_add_f32_e32 v16, 1.0, v16
	v_add_f32_e32 v17, 1.0, v17
	v_rcp_f32_e32 v16, v16
	v_rcp_f32_e32 v17, v17
	v_lshl_add_u64 v[32:33], v[32:33], 0, v[134:135]
	v_pk_mul_f32 v[16:17], v[28:29], v[16:17]
	s_nop 0
	v_pk_mul_f32 v[16:17], v[20:21], v[16:17]
	s_nop 0
	v_cvt_pk_bf16_f32 v16, v16, v17
	v_mul_f32_e32 v17, 0xbfb8aa3b, v30
	v_exp_f32_e32 v17, v17
	s_nop 0
	v_add_f32_e32 v17, 1.0, v17
	v_rcp_f32_e32 v20, v17
	v_mul_f32_e32 v17, 0xbfb8aa3b, v31
	v_exp_f32_e32 v17, v17
	s_nop 0
	v_add_f32_e32 v17, 1.0, v17
	v_rcp_f32_e32 v21, v17
	s_nop 0
	v_pk_mul_f32 v[20:21], v[30:31], v[20:21]
	s_nop 0
	v_pk_mul_f32 v[20:21], v[22:23], v[20:21]
	s_nop 0
	v_cvt_pk_bf16_f32 v17, v20, v21
	v_mul_f32_e32 v20, 0xbfb8aa3b, v24
	v_mul_f32_e32 v21, 0xbfb8aa3b, v25
	v_exp_f32_e32 v20, v20
	v_exp_f32_e32 v21, v21
	v_add_f32_e32 v20, 1.0, v20
	v_add_f32_e32 v21, 1.0, v21
	v_rcp_f32_e32 v20, v20
	v_rcp_f32_e32 v21, v21
	s_nop 0
	v_pk_mul_f32 v[20:21], v[24:25], v[20:21]
	s_nop 0
	v_pk_mul_f32 v[18:19], v[18:19], v[20:21]
	s_nop 0
	v_cvt_pk_bf16_f32 v18, v18, v19
	v_mul_f32_e32 v19, 0xbfb8aa3b, v26
	v_exp_f32_e32 v19, v19
	s_nop 0
	v_add_f32_e32 v19, 1.0, v19
	v_rcp_f32_e32 v20, v19
	v_mul_f32_e32 v19, 0xbfb8aa3b, v27
	v_exp_f32_e32 v19, v19
	s_nop 0
	v_add_f32_e32 v19, 1.0, v19
	v_rcp_f32_e32 v21, v19
	s_nop 0
	v_pk_mul_f32 v[20:21], v[26:27], v[20:21]
	s_nop 0
	v_pk_mul_f32 v[20:21], v[34:35], v[20:21]
	s_nop 0
	v_cvt_pk_bf16_f32 v19, v20, v21
	global_store_dwordx4 v[32:33], v[16:19], off
	s_nop 1
	v_pk_mul_f32 v[18:19], v[2:3], v[130:131] op_sel_hi:[1,0]
	v_pk_mul_f32 v[2:3], v[0:1], v[130:131] op_sel_hi:[1,0]
	v_mul_f32_e32 v0, 0xbfb8aa3b, v12
	v_mul_f32_e32 v1, 0xbfb8aa3b, v13
	v_exp_f32_e32 v0, v0
	v_exp_f32_e32 v1, v1
	v_add_u32_e32 v16, 0xb0, v210
	v_mad_i64_i32 v[16:17], s[0:1], v16, s2, v[132:133]
	v_add_f32_e32 v0, 1.0, v0
	v_add_f32_e32 v1, 1.0, v1
	v_rcp_f32_e32 v0, v0
	v_rcp_f32_e32 v1, v1
	v_lshl_add_u64 v[16:17], v[16:17], 0, v[134:135]
	s_mov_b64 s[0:1], -1
	v_pk_mul_f32 v[0:1], v[12:13], v[0:1]
	s_nop 0
	v_pk_mul_f32 v[0:1], v[4:5], v[0:1]
	s_nop 0
	v_cvt_pk_bf16_f32 v0, v0, v1
	v_mul_f32_e32 v1, 0xbfb8aa3b, v14
	v_exp_f32_e32 v1, v1
	s_nop 0
	v_add_f32_e32 v1, 1.0, v1
	v_rcp_f32_e32 v4, v1
	v_mul_f32_e32 v1, 0xbfb8aa3b, v15
	v_exp_f32_e32 v1, v1
	s_nop 0
	v_add_f32_e32 v1, 1.0, v1
	v_rcp_f32_e32 v5, v1
	s_nop 0
	v_pk_mul_f32 v[4:5], v[14:15], v[4:5]
	s_nop 0
	v_pk_mul_f32 v[4:5], v[6:7], v[4:5]
	s_nop 0
	v_cvt_pk_bf16_f32 v1, v4, v5
	v_mul_f32_e32 v4, 0xbfb8aa3b, v8
	v_mul_f32_e32 v5, 0xbfb8aa3b, v9
	v_exp_f32_e32 v4, v4
	v_exp_f32_e32 v5, v5
	v_add_f32_e32 v4, 1.0, v4
	v_add_f32_e32 v5, 1.0, v5
	v_rcp_f32_e32 v4, v4
	v_rcp_f32_e32 v5, v5
	s_nop 0
	v_pk_mul_f32 v[4:5], v[8:9], v[4:5]
	s_nop 0
	v_pk_mul_f32 v[2:3], v[2:3], v[4:5]
	s_nop 0
	v_cvt_pk_bf16_f32 v2, v2, v3
	v_mul_f32_e32 v3, 0xbfb8aa3b, v10
	v_exp_f32_e32 v3, v3
	s_nop 0
	v_add_f32_e32 v3, 1.0, v3
	v_rcp_f32_e32 v4, v3
	v_mul_f32_e32 v3, 0xbfb8aa3b, v11
	v_exp_f32_e32 v3, v3
	s_nop 0
	v_add_f32_e32 v3, 1.0, v3
	v_rcp_f32_e32 v5, v3
	s_nop 0
	v_pk_mul_f32 v[4:5], v[10:11], v[4:5]
	s_nop 0
	v_pk_mul_f32 v[4:5], v[18:19], v[4:5]
	s_nop 0
	v_cvt_pk_bf16_f32 v3, v4, v5
	global_store_dwordx4 v[16:17], v[0:3], off
	s_branch .Lswi_join
